# LN1/LN2: loads of rows 1-3 of each 4-row iteration hoisted to the iteration top (counted vmcnt), on top of deferred sample units + batched fold
# baseline (speedup 1.0000x reference)
; __device__ __forceinline__ void unpack8(u32x4 w, f32x4& a, f32x4& b) { a = (f32x4){bflo(w.x), bfhi(w.x), bflo(w.y), bfhi(w.y)}; b = (f32x4){bflo(w.z), bfhi(w.z), bflo(w.w), bfhi(w.w)}; }
; #define lane lane_id_asm()
; template <int NR> __device__ __forceinline__ void ln_rows(const bf16* (&zr)[NR], bf16* (&ob)[NR], float* (&of)[NR], const float* g, const float* bt, int lane) {
;     f32x4 v[NR][4];
; #pragma unroll
;     for (int r = 0; r < NR; ++r) { const v4u w0 = __builtin_nontemporal_load((const v4u*)zr[r] + lane), w1 = __builtin_nontemporal_load((const v4u*)zr[r] + 64 + lane); epi::unpack8(w0, v[r][0], v[r][1]); epi::unpack8(w1, v[r][2], v[r][3]); }
;     f32x4 gg[4], bb[4];
; #pragma unroll
;     for (int j = 0; j < 4; ++j) { gg[j] = *((const f32x4*)g + (j >> 1) * 128 + 2 * lane + (j & 1)); bb[j] = *((const f32x4*)bt + (j >> 1) * 128 + 2 * lane + (j & 1)); }
; #pragma unroll
;     for (int r = 0; r < NR; ++r) { float s = 0.f;
; #pragma unroll
;         for (int j = 0; j < 4; ++j) s += (v[r][j].x + v[r][j].y) + (v[r][j].z + v[r][j].w);
;         const float mean = wave_sum(s) * (1.f / 1024.f); float s2 = 0.f;
; #pragma unroll
;         for (int j = 0; j < 4; ++j) { v[r][j] = v[r][j] - mean; s2 += (v[r][j].x * v[r][j].x + v[r][j].y * v[r][j].y) + (v[r][j].z * v[r][j].z + v[r][j].w * v[r][j].w); }
;         const float rstd = 1.f / sqrtf(wave_sum(s2) * (1.f / 1024.f) + LN_EPS);
.LBB0_1070:
	s_ashr_i32 s9, s8, 31
	s_lshl_b64 s[46:47], s[8:9], 11
	v_lshl_add_u64 v[0:1], v[52:53], 0, s[46:47]
	global_load_dwordx4 v[44:47], v[0:1], off nt
	s_nop 0
	global_load_dwordx4 v[0:3], v[0:1], off offset:1024 nt
	s_sub_i32 s12, s4, s18
	s_ashr_i32 s13, s12, 31
	s_lshl_b64 s[44:45], s[12:13], 11
	s_add_i32 s14, s12, s33
	s_ashr_i32 s15, s14, 31
	s_lshl_b64 s[14:15], s[14:15], 11
	s_ashr_i32 s5, s4, 31
	s_lshl_b64 s[4:5], s[4:5], 11
	v_lshl_add_u64 v[212:213], v[52:53], 0, s[44:45]
	global_load_dwordx4 v[40:43], v[212:213], off nt
	global_load_dwordx4 v[200:203], v[212:213], off offset:1024 nt
	v_lshl_add_u64 v[212:213], v[52:53], 0, s[14:15]
	global_load_dwordx4 v[36:39], v[212:213], off nt
	global_load_dwordx4 v[204:207], v[212:213], off offset:1024 nt
	v_lshl_add_u64 v[212:213], v[52:53], 0, s[4:5]
	global_load_dwordx4 v[32:35], v[212:213], off nt
	global_load_dwordx4 v[208:211], v[212:213], off offset:1024 nt
	v_cmp_lt_i32_e32 vcc, v110, v109
	s_waitcnt vmcnt(6)
	v_lshlrev_b32_e32 v105, 16, v45
	v_lshlrev_b32_e32 v96, 16, v0
	v_and_b32_e32 v97, 0xffff0000, v0
	v_lshlrev_b32_e32 v98, 16, v1
	v_and_b32_e32 v99, 0xffff0000, v1
	v_lshlrev_b32_e32 v94, 16, v2
	v_and_b32_e32 v102, 0xffff0000, v2
	v_lshlrev_b32_e32 v92, 16, v3
	v_and_b32_e32 v100, 0xffff0000, v3
	v_lshlrev_b32_e32 v104, 16, v44
	v_and_b32_e32 v123, 0xffff0000, v45
	v_and_b32_e32 v122, 0xffff0000, v44
	v_pk_add_f32 v[44:45], v[104:105], v[122:123]
	v_and_b32_e32 v125, 0xffff0000, v47
	v_add_f32_e32 v44, v44, v45
	v_add_f32_e32 v101, 0, v44
	v_lshlrev_b32_e32 v45, 16, v47
	v_lshlrev_b32_e32 v44, 16, v46
	v_and_b32_e32 v124, 0xffff0000, v46
	v_pk_add_f32 v[46:47], v[44:45], v[124:125]
	v_add_f32_e32 v95, v96, v97
	v_pk_add_f32 v[46:47], v[46:47], v[46:47] op_sel_hi:[0,1]
	v_add_f32_e32 v103, v98, v99
	v_mov_b32_e32 v93, v47
	v_pk_add_f32 v[126:127], v[94:95], v[102:103]
	v_pk_add_f32 v[46:47], v[92:93], v[100:101]
	v_cndmask_b32_e32 v57, v108, v110, vcc
	v_pk_add_f32 v[46:47], v[126:127], v[46:47]
	v_lshlrev_b32_e32 v121, 2, v57
	v_add_f32_e32 v46, v46, v47
	ds_bpermute_b32 v47, v121, v46
	v_cmp_lt_i32_e32 vcc, v111, v109
	s_waitcnt lgkmcnt(0)
	v_add_f32_e32 v46, v46, v47
	v_cndmask_b32_e32 v57, v108, v111, vcc
	v_lshlrev_b32_e32 v120, 2, v57
	ds_bpermute_b32 v47, v120, v46
	v_cmp_lt_i32_e32 vcc, v112, v109
	s_waitcnt lgkmcnt(0)
	v_add_f32_e32 v46, v46, v47
	v_cndmask_b32_e32 v57, v108, v112, vcc
	v_lshlrev_b32_e32 v119, 2, v57
	ds_bpermute_b32 v47, v119, v46
	v_cmp_lt_i32_e32 vcc, v113, v109
	s_waitcnt lgkmcnt(0)
	v_add_f32_e32 v46, v46, v47
	v_cndmask_b32_e32 v57, v108, v113, vcc
	v_lshlrev_b32_e32 v118, 2, v57
	ds_bpermute_b32 v47, v118, v46
	v_cmp_lt_i32_e32 vcc, v114, v109
	s_waitcnt lgkmcnt(0)
	v_add_f32_e32 v46, v46, v47
	v_cndmask_b32_e32 v57, v108, v114, vcc
	v_lshlrev_b32_e32 v117, 2, v57
	ds_bpermute_b32 v47, v117, v46
	v_cmp_lt_i32_e32 vcc, v115, v109
	s_waitcnt lgkmcnt(0)
	v_add_f32_e32 v46, v46, v47
	v_cndmask_b32_e32 v57, v108, v115, vcc
	v_lshlrev_b32_e32 v116, 2, v57
	ds_bpermute_b32 v47, v116, v46
	s_waitcnt lgkmcnt(0)
	v_add_f32_e32 v57, v46, v47
	v_fmac_f32_e32 v122, 0xba800000, v57
	v_fmac_f32_e32 v123, 0xba800000, v57
	v_fmac_f32_e32 v105, 0xba800000, v57
	v_fmac_f32_e32 v104, 0xba800000, v57
	v_mov_b32_e32 v46, v105
	v_mov_b32_e32 v47, v123
	v_mov_b32_e32 v105, v122
	v_pk_mul_f32 v[126:127], v[46:47], v[46:47]
	v_pk_mul_f32 v[122:123], v[104:105], v[104:105]
	v_fmac_f32_e32 v124, 0xba800000, v57
	v_pk_mov_b32 v[128:129], v[122:123], v[126:127] op_sel:[1,0]
	v_mov_b32_e32 v123, v127
	s_waitcnt vmcnt(4)
	v_lshlrev_b32_e32 v84, 16, v200
	v_and_b32_e32 v85, 0xffff0000, v200
	v_lshlrev_b32_e32 v86, 16, v201
	v_and_b32_e32 v87, 0xffff0000, v201
	v_lshlrev_b32_e32 v82, 16, v202
	v_and_b32_e32 v90, 0xffff0000, v202
	v_lshlrev_b32_e32 v80, 16, v203
	v_and_b32_e32 v88, 0xffff0000, v203
	v_fmac_f32_e32 v125, 0xba800000, v57
	v_fmac_f32_e32 v45, 0xba800000, v57
	v_pk_add_f32 v[122:123], v[128:129], v[122:123]
	v_fmac_f32_e32 v44, 0xba800000, v57
	v_mov_b32_e32 v126, v45
	v_mov_b32_e32 v127, v125
	v_mov_b32_e32 v45, v124
	v_pk_add_f32 v[122:123], v[122:123], v[122:123] op_sel_hi:[0,1]
	v_pk_mul_f32 v[128:129], v[126:127], v[126:127]
	v_pk_mul_f32 v[124:125], v[44:45], v[44:45]
	v_fmac_f32_e32 v96, 0xba800000, v57
	v_pk_mov_b32 v[130:131], v[124:125], v[128:129] op_sel:[1,0]
	v_mov_b32_e32 v125, v129
	v_fmac_f32_e32 v97, 0xba800000, v57
	v_fmac_f32_e32 v98, 0xba800000, v57
	v_mul_f32_e32 v122, v96, v96
	v_pk_add_f32 v[124:125], v[130:131], v[124:125]
	v_fmac_f32_e32 v99, 0xba800000, v57
	v_pk_fma_f32 v[128:129], v[96:97], v[96:97], v[122:123] op_sel_hi:[1,1,0]
	v_mul_f32_e32 v122, v98, v98
	v_pk_add_f32 v[124:125], v[124:125], v[124:125] op_sel_hi:[0,1]
	v_pk_fma_f32 v[130:131], v[98:99], v[98:99], v[122:123] op_sel_hi:[1,1,0]
	v_fmac_f32_e32 v100, 0xba800000, v57
	v_fmac_f32_e32 v92, 0xba800000, v57
	v_fmac_f32_e32 v102, 0xba800000, v57
	v_fmac_f32_e32 v94, 0xba800000, v57
	v_mul_f32_e32 v128, v94, v94
	v_mul_f32_e32 v130, v102, v102
	v_mul_f32_e32 v122, v92, v92
	v_mul_f32_e32 v124, v100, v100
	v_pk_add_f32 v[128:129], v[128:129], v[130:131]
	v_pk_add_f32 v[122:123], v[122:123], v[124:125]
	v_mov_b32_e32 v95, v102
	v_pk_add_f32 v[122:123], v[128:129], v[122:123]
	v_mov_b32_e32 v93, v100
	v_add_f32_e32 v57, v122, v123
	ds_bpermute_b32 v59, v121, v57
	v_lshl_add_u64 v[100:101], v[54:55], 0, s[46:47]
	v_add_f32_e32 v83, v84, v85
	v_add_f32_e32 v91, v86, v87
	s_waitcnt lgkmcnt(0)
	v_add_f32_e32 v57, v57, v59
	ds_bpermute_b32 v59, v120, v57
	s_waitcnt lgkmcnt(0)
	v_add_f32_e32 v57, v57, v59
	ds_bpermute_b32 v59, v119, v57
	s_waitcnt lgkmcnt(0)
; __device__ __forceinline__ u32x4 pack8(f32x4 a, f32x4 b) { u32x4 w; w.x = cvt_pk_bf16(a[0], a[1]); w.y = cvt_pk_bf16(a[2], a[3]); w.z = cvt_pk_bf16(b[0], b[1]); w.w = cvt_pk_bf16(b[2], b[3]); return w; }
; #define lane lane_id_asm()
; template <int NR> __device__ __forceinline__ void ln_rows(const bf16* (&zr)[NR], bf16* (&ob)[NR], float* (&of)[NR], const float* g, const float* bt, int lane) {
;     ...
;     for (int r = 0; r < NR; ++r) { float s = 0.f;
; #pragma unroll
;         for (int j = 0; j < 4; ++j) s += (v[r][j].x + v[r][j].y) + (v[r][j].z + v[r][j].w);
;         const float mean = wave_sum(s) * (1.f / 1024.f); float s2 = 0.f;
; #pragma unroll
;         for (int j = 0; j < 4; ++j) { v[r][j] = v[r][j] - mean; s2 += (v[r][j].x * v[r][j].x + v[r][j].y * v[r][j].y) + (v[r][j].z * v[r][j].z + v[r][j].w * v[r][j].w); }
;         const float rstd = 1.f / sqrtf(wave_sum(s2) * (1.f / 1024.f) + LN_EPS);
; #pragma unroll
;         for (int j = 0; j < 4; ++j) v[r][j] = v[r][j] * rstd * gg[j] + bb[j];
;         if (ob[r]) { *((v4u*)ob[r] + lane) = epi::pack8(v[r][0], v[r][1]); *((v4u*)ob[r] + 64 + lane) = epi::pack8(v[r][2], v[r][3]); }
	v_add_f32_e32 v57, v57, v59
	ds_bpermute_b32 v59, v118, v57
	s_waitcnt lgkmcnt(0)
	v_add_f32_e32 v57, v57, v59
	ds_bpermute_b32 v59, v117, v57
	s_waitcnt lgkmcnt(0)
	v_add_f32_e32 v57, v57, v59
	ds_bpermute_b32 v59, v116, v57
	s_waitcnt lgkmcnt(0)
	v_add_f32_e32 v57, v57, v59
	v_fmamk_f32 v57, v57, 0x3a800000, v106
	v_cmp_gt_f32_e32 vcc, s19, v57
	v_mul_f32_e32 v59, 0x4f800000, v57
	s_waitcnt vmcnt(2)
	v_lshlrev_b32_e32 v72, 16, v204
	v_and_b32_e32 v73, 0xffff0000, v204
	v_lshlrev_b32_e32 v74, 16, v205
	v_and_b32_e32 v75, 0xffff0000, v205
	v_lshlrev_b32_e32 v70, 16, v206
	v_and_b32_e32 v78, 0xffff0000, v206
	v_lshlrev_b32_e32 v68, 16, v207
	v_and_b32_e32 v76, 0xffff0000, v207
	v_cndmask_b32_e32 v57, v57, v59, vcc
	v_sqrt_f32_e32 v59, v57
	v_add_f32_e32 v79, v74, v75
	v_add_u32_e32 v61, -1, v59
	v_fma_f32 v65, -v61, v59, v57
	v_cmp_ge_f32_e64 s[42:43], 0, v65
	v_add_u32_e32 v65, 1, v59
	s_waitcnt vmcnt(0)
	v_lshlrev_b32_e32 v62, 16, v208
	v_and_b32_e32 v63, 0xffff0000, v208
	v_lshlrev_b32_e32 v66, 16, v209
	v_and_b32_e32 v67, 0xffff0000, v209
	v_lshlrev_b32_e32 v58, 16, v210
	v_and_b32_e32 v64, 0xffff0000, v210
	v_lshlrev_b32_e32 v56, 16, v211
	v_and_b32_e32 v60, 0xffff0000, v211
	global_load_dwordx4 v[8:11], v[48:49], off offset:16
	global_load_dwordx4 v[24:27], v[48:49], off
	global_load_dwordx4 v[16:19], v[50:51], off offset:16
	global_load_dwordx4 v[28:31], v[50:51], off
	global_load_dwordx4 v[0:3], v[48:49], off offset:2064
	global_load_dwordx4 v[12:15], v[48:49], off offset:2048
	global_load_dwordx4 v[4:7], v[50:51], off offset:2064
	global_load_dwordx4 v[20:23], v[50:51], off offset:2048
	v_cndmask_b32_e64 v61, v59, v61, s[42:43]
	v_fma_f32 v59, -v65, v59, v57
	v_cmp_lt_f32_e64 s[42:43], 0, v59
	s_nop 1
	v_cndmask_b32_e64 v59, v61, v65, s[42:43]
	v_mul_f32_e32 v61, 0x37800000, v59
	v_cndmask_b32_e32 v59, v59, v61, vcc
	v_cmp_class_f32_e32 vcc, v57, v107
	s_nop 1
	v_cndmask_b32_e32 v57, v59, v57, vcc
	v_div_scale_f32 v59, s[12:13], v57, v57, 1.0
	v_rcp_f32_e32 v61, v59
	s_nop 0
	v_fma_f32 v65, -v59, v61, 1.0
	v_fmac_f32_e32 v61, v65, v61
	v_div_scale_f32 v65, vcc, 1.0, v57, 1.0
	v_mul_f32_e32 v69, v65, v61
	v_fma_f32 v71, -v59, v69, v65
	v_fmac_f32_e32 v69, v71, v61
	v_fma_f32 v59, -v59, v69, v65
	v_div_fmas_f32 v59, v59, v61, v69
	v_div_fixup_f32 v122, v59, v57, 1.0
	v_pk_mul_f32 v[44:45], v[44:45], v[122:123] op_sel_hi:[1,0]
	v_pk_mul_f32 v[46:47], v[46:47], v[122:123] op_sel_hi:[1,0]
	v_pk_mul_f32 v[124:125], v[126:127], v[122:123] op_sel_hi:[1,0]
	v_pk_mul_f32 v[104:105], v[104:105], v[122:123] op_sel_hi:[1,0]
	v_pk_mul_f32 v[92:93], v[92:93], v[122:123] op_sel_hi:[1,0]
	v_add_f32_e32 v71, v72, v73
	v_add_f32_e32 v65, v66, v67
	s_waitcnt vmcnt(5)
	v_pk_fma_f32 v[126:127], v[8:9], v[44:45], v[16:17]
	v_pk_mul_f32 v[44:45], v[96:97], v[122:123] op_sel_hi:[1,0]
	s_waitcnt vmcnt(4)
	v_pk_fma_f32 v[46:47], v[26:27], v[46:47], v[30:31]
	v_pk_mul_f32 v[96:97], v[98:99], v[122:123] op_sel_hi:[1,0]
	v_pk_fma_f32 v[104:105], v[24:25], v[104:105], v[28:29]
	s_waitcnt vmcnt(0)
	v_pk_fma_f32 v[98:99], v[12:13], v[44:45], v[20:21]
	v_pk_mul_f32 v[44:45], v[94:95], v[122:123] op_sel_hi:[1,0]
	v_pk_fma_f32 v[124:125], v[10:11], v[124:125], v[18:19]
	v_pk_fma_f32 v[94:95], v[0:1], v[44:45], v[4:5]
	v_cvt_pk_bf16_f32 v44, v104, v105
	v_cvt_pk_bf16_f32 v45, v46, v47
	v_cvt_pk_bf16_f32 v46, v126, v127
	v_cvt_pk_bf16_f32 v47, v124, v125
	v_pk_fma_f32 v[96:97], v[14:15], v[96:97], v[22:23]
	v_pk_fma_f32 v[92:93], v[2:3], v[92:93], v[6:7]
	global_store_dwordx4 v[100:101], v[44:47], off
	s_nop 1
	v_cvt_pk_bf16_f32 v44, v98, v99
	v_cvt_pk_bf16_f32 v45, v96, v97
	v_cvt_pk_bf16_f32 v46, v94, v95
	v_cvt_pk_bf16_f32 v47, v92, v93
	global_store_dwordx4 v[100:101], v[44:47], off offset:1024
	v_pk_add_f32 v[94:95], v[82:83], v[90:91]
	s_nop 0
	v_lshlrev_b32_e32 v45, 16, v41
	v_lshlrev_b32_e32 v44, 16, v40
	v_and_b32_e32 v47, 0xffff0000, v41
	v_and_b32_e32 v46, 0xffff0000, v40
	v_pk_add_f32 v[40:41], v[44:45], v[46:47]
	s_nop 0
	v_add_f32_e32 v40, v40, v41
	v_add_f32_e32 v89, 0, v40
	v_lshlrev_b32_e32 v41, 16, v43
	v_lshlrev_b32_e32 v40, 16, v42
	v_and_b32_e32 v43, 0xffff0000, v43
	v_and_b32_e32 v42, 0xffff0000, v42
	v_pk_add_f32 v[92:93], v[40:41], v[42:43]
	s_nop 0
	v_pk_add_f32 v[92:93], v[92:93], v[92:93] op_sel_hi:[0,1]
	v_mov_b32_e32 v81, v93
	v_pk_add_f32 v[92:93], v[80:81], v[88:89]
	s_nop 0
	v_pk_add_f32 v[92:93], v[94:95], v[92:93]
	s_nop 0
	v_add_f32_e32 v57, v92, v93
	ds_bpermute_b32 v59, v121, v57
	s_waitcnt lgkmcnt(0)
	v_add_f32_e32 v57, v57, v59
	ds_bpermute_b32 v59, v120, v57
	s_waitcnt lgkmcnt(0)
	v_add_f32_e32 v57, v57, v59
	ds_bpermute_b32 v59, v119, v57
	s_waitcnt lgkmcnt(0)
	v_add_f32_e32 v57, v57, v59
	ds_bpermute_b32 v59, v118, v57
	s_waitcnt lgkmcnt(0)
	v_add_f32_e32 v57, v57, v59
	ds_bpermute_b32 v59, v117, v57
	s_waitcnt lgkmcnt(0)
	v_add_f32_e32 v57, v57, v59
	ds_bpermute_b32 v59, v116, v57
	s_waitcnt lgkmcnt(0)
; __device__ __forceinline__ u32x4 pack8(f32x4 a, f32x4 b) { u32x4 w; w.x = cvt_pk_bf16(a[0], a[1]); w.y = cvt_pk_bf16(a[2], a[3]); w.z = cvt_pk_bf16(b[0], b[1]); w.w = cvt_pk_bf16(b[2], b[3]); return w; }
; #define lane lane_id_asm()
; template <int NR> __device__ __forceinline__ void ln_rows(const bf16* (&zr)[NR], bf16* (&ob)[NR], float* (&of)[NR], const float* g, const float* bt, int lane) {
;     ...
;     for (int r = 0; r < NR; ++r) { float s = 0.f;
; #pragma unroll
;         for (int j = 0; j < 4; ++j) s += (v[r][j].x + v[r][j].y) + (v[r][j].z + v[r][j].w);
;         const float mean = wave_sum(s) * (1.f / 1024.f); float s2 = 0.f;
; #pragma unroll
;         for (int j = 0; j < 4; ++j) { v[r][j] = v[r][j] - mean; s2 += (v[r][j].x * v[r][j].x + v[r][j].y * v[r][j].y) + (v[r][j].z * v[r][j].z + v[r][j].w * v[r][j].w); }
;         const float rstd = 1.f / sqrtf(wave_sum(s2) * (1.f / 1024.f) + LN_EPS);
; #pragma unroll
;         for (int j = 0; j < 4; ++j) v[r][j] = v[r][j] * rstd * gg[j] + bb[j];
;         if (ob[r]) { *((v4u*)ob[r] + lane) = epi::pack8(v[r][0], v[r][1]); *((v4u*)ob[r] + 64 + lane) = epi::pack8(v[r][2], v[r][3]); }
	v_add_f32_e32 v57, v57, v59
	v_fmac_f32_e32 v46, 0xba800000, v57
	v_fmac_f32_e32 v47, 0xba800000, v57
	v_fmac_f32_e32 v45, 0xba800000, v57
	v_fmac_f32_e32 v44, 0xba800000, v57
	v_mov_b32_e32 v92, v45
	v_mov_b32_e32 v93, v47
	v_mov_b32_e32 v45, v46
	v_pk_mul_f32 v[94:95], v[92:93], v[92:93]
	v_pk_mul_f32 v[46:47], v[44:45], v[44:45]
	v_fmac_f32_e32 v42, 0xba800000, v57
	v_fmac_f32_e32 v43, 0xba800000, v57
	v_fmac_f32_e32 v41, 0xba800000, v57
	v_pk_mov_b32 v[96:97], v[46:47], v[94:95] op_sel:[1,0]
	v_mov_b32_e32 v47, v95
	v_fmac_f32_e32 v40, 0xba800000, v57
	v_mov_b32_e32 v94, v41
	v_mov_b32_e32 v95, v43
	v_mov_b32_e32 v41, v42
	v_pk_add_f32 v[46:47], v[96:97], v[46:47]
	v_pk_mul_f32 v[96:97], v[94:95], v[94:95]
	v_pk_mul_f32 v[42:43], v[40:41], v[40:41]
	v_fmac_f32_e32 v84, 0xba800000, v57
	v_pk_mov_b32 v[98:99], v[42:43], v[96:97] op_sel:[1,0]
	v_mov_b32_e32 v43, v97
	v_pk_add_f32 v[42:43], v[98:99], v[42:43]
	v_fmac_f32_e32 v85, 0xba800000, v57
	v_pk_add_f32 v[42:43], v[42:43], v[42:43] op_sel_hi:[0,1]
	v_fmac_f32_e32 v86, 0xba800000, v57
	v_mul_f32_e32 v42, v84, v84
	v_fmac_f32_e32 v87, 0xba800000, v57
	v_pk_fma_f32 v[96:97], v[84:85], v[84:85], v[42:43] op_sel_hi:[1,1,0]
	v_mul_f32_e32 v42, v86, v86
	v_pk_add_f32 v[46:47], v[46:47], v[46:47] op_sel_hi:[0,1]
	v_pk_fma_f32 v[98:99], v[86:87], v[86:87], v[42:43] op_sel_hi:[1,1,0]
	v_fmac_f32_e32 v88, 0xba800000, v57
	v_fmac_f32_e32 v80, 0xba800000, v57
	v_fmac_f32_e32 v90, 0xba800000, v57
	v_fmac_f32_e32 v82, 0xba800000, v57
	v_mul_f32_e32 v96, v82, v82
	v_mul_f32_e32 v98, v90, v90
	v_mul_f32_e32 v46, v80, v80
	v_mul_f32_e32 v42, v88, v88
	v_pk_add_f32 v[96:97], v[96:97], v[98:99]
	v_pk_add_f32 v[42:43], v[46:47], v[42:43]
	v_mov_b32_e32 v83, v90
	v_pk_add_f32 v[42:43], v[96:97], v[42:43]
	v_mov_b32_e32 v81, v88
	v_add_f32_e32 v42, v42, v43
	ds_bpermute_b32 v43, v121, v42
	s_waitcnt lgkmcnt(0)
	v_add_f32_e32 v42, v42, v43
	ds_bpermute_b32 v43, v120, v42
	s_waitcnt lgkmcnt(0)
	v_add_f32_e32 v42, v42, v43
	ds_bpermute_b32 v43, v119, v42
	s_waitcnt lgkmcnt(0)
	v_add_f32_e32 v42, v42, v43
	ds_bpermute_b32 v43, v118, v42
	s_waitcnt lgkmcnt(0)
	v_add_f32_e32 v42, v42, v43
	ds_bpermute_b32 v43, v117, v42
	s_waitcnt lgkmcnt(0)
	v_add_f32_e32 v42, v42, v43
	ds_bpermute_b32 v43, v116, v42
	s_waitcnt lgkmcnt(0)
	v_add_f32_e32 v42, v42, v43
	v_fmamk_f32 v42, v42, 0x3a800000, v106
	v_cmp_gt_f32_e32 vcc, s19, v42
	v_mul_f32_e32 v43, 0x4f800000, v42
	s_nop 0
	v_cndmask_b32_e32 v42, v42, v43, vcc
	v_sqrt_f32_e32 v43, v42
	s_nop 0
	v_add_u32_e32 v46, -1, v43
	v_fma_f32 v47, -v46, v43, v42
	v_cmp_ge_f32_e64 s[42:43], 0, v47
	v_add_u32_e32 v47, 1, v43
	s_nop 0
	v_cndmask_b32_e64 v46, v43, v46, s[42:43]
	v_fma_f32 v43, -v47, v43, v42
	v_cmp_lt_f32_e64 s[42:43], 0, v43
	s_nop 1
	v_cndmask_b32_e64 v43, v46, v47, s[42:43]
	v_mul_f32_e32 v46, 0x37800000, v43
	v_cndmask_b32_e32 v43, v43, v46, vcc
	v_cmp_class_f32_e32 vcc, v42, v107
	s_nop 1
	v_cndmask_b32_e32 v42, v43, v42, vcc
	v_div_scale_f32 v43, s[12:13], v42, v42, 1.0
	v_rcp_f32_e32 v46, v43
	s_nop 0
	v_fma_f32 v47, -v43, v46, 1.0
	v_fmac_f32_e32 v46, v47, v46
	v_div_scale_f32 v47, vcc, 1.0, v42, 1.0
	v_mul_f32_e32 v57, v47, v46
	v_fma_f32 v59, -v43, v57, v47
	v_fmac_f32_e32 v57, v59, v46
	v_fma_f32 v43, -v43, v57, v47
	v_div_fmas_f32 v43, v43, v46, v57
	v_div_fixup_f32 v42, v43, v42, 1.0
	v_pk_mul_f32 v[40:41], v[40:41], v[42:43] op_sel_hi:[1,0]
	v_pk_mul_f32 v[44:45], v[44:45], v[42:43] op_sel_hi:[1,0]
	v_pk_mul_f32 v[46:47], v[92:93], v[42:43] op_sel_hi:[1,0]
	v_pk_mul_f32 v[92:93], v[94:95], v[42:43] op_sel_hi:[1,0]
	v_pk_fma_f32 v[94:95], v[8:9], v[40:41], v[16:17]
	v_pk_mul_f32 v[40:41], v[84:85], v[42:43] op_sel_hi:[1,0]
	v_pk_fma_f32 v[44:45], v[24:25], v[44:45], v[28:29]
	v_pk_mul_f32 v[84:85], v[86:87], v[42:43] op_sel_hi:[1,0]
	v_pk_fma_f32 v[86:87], v[12:13], v[40:41], v[20:21]
	v_pk_mul_f32 v[40:41], v[82:83], v[42:43] op_sel_hi:[1,0]
	v_pk_mul_f32 v[42:43], v[80:81], v[42:43] op_sel_hi:[1,0]
	v_pk_fma_f32 v[46:47], v[26:27], v[46:47], v[30:31]
	v_pk_fma_f32 v[92:93], v[10:11], v[92:93], v[18:19]
	v_pk_fma_f32 v[80:81], v[2:3], v[42:43], v[6:7]
	v_pk_fma_f32 v[82:83], v[0:1], v[40:41], v[4:5]
	v_cvt_pk_bf16_f32 v40, v44, v45
	v_cvt_pk_bf16_f32 v41, v46, v47
	v_cvt_pk_bf16_f32 v42, v94, v95
	v_cvt_pk_bf16_f32 v43, v92, v93
	v_lshl_add_u64 v[44:45], v[54:55], 0, s[44:45]
	v_pk_fma_f32 v[84:85], v[14:15], v[84:85], v[22:23]
	global_store_dwordx4 v[44:45], v[40:43], off
	v_pk_add_f32 v[46:47], v[70:71], v[78:79]
	s_nop 0
	v_cvt_pk_bf16_f32 v40, v86, v87
	v_cvt_pk_bf16_f32 v41, v84, v85
	v_cvt_pk_bf16_f32 v42, v82, v83
	v_cvt_pk_bf16_f32 v43, v80, v81
	global_store_dwordx4 v[44:45], v[40:43], off offset:1024
	s_nop 1
	v_lshlrev_b32_e32 v41, 16, v37
	v_lshlrev_b32_e32 v40, 16, v36
	v_and_b32_e32 v43, 0xffff0000, v37
	v_and_b32_e32 v42, 0xffff0000, v36
	v_pk_add_f32 v[36:37], v[40:41], v[42:43]
	s_nop 0
	v_add_f32_e32 v36, v36, v37
	v_add_f32_e32 v77, 0, v36
	v_lshlrev_b32_e32 v37, 16, v39
	v_lshlrev_b32_e32 v36, 16, v38
	v_and_b32_e32 v39, 0xffff0000, v39
	v_and_b32_e32 v38, 0xffff0000, v38
	v_pk_add_f32 v[44:45], v[36:37], v[38:39]
	s_nop 0
	v_pk_add_f32 v[44:45], v[44:45], v[44:45] op_sel_hi:[0,1]
	v_mov_b32_e32 v69, v45
	v_pk_add_f32 v[44:45], v[68:69], v[76:77]
	s_nop 0
	v_pk_add_f32 v[44:45], v[46:47], v[44:45]
	s_nop 0
	v_add_f32_e32 v44, v44, v45
	ds_bpermute_b32 v45, v121, v44
	s_waitcnt lgkmcnt(0)
	v_add_f32_e32 v44, v44, v45
	ds_bpermute_b32 v45, v120, v44
	s_waitcnt lgkmcnt(0)
	v_add_f32_e32 v44, v44, v45
	ds_bpermute_b32 v45, v119, v44
	s_waitcnt lgkmcnt(0)
	v_add_f32_e32 v44, v44, v45
	ds_bpermute_b32 v45, v118, v44
	s_waitcnt lgkmcnt(0)
; __device__ __forceinline__ u32x4 pack8(f32x4 a, f32x4 b) { u32x4 w; w.x = cvt_pk_bf16(a[0], a[1]); w.y = cvt_pk_bf16(a[2], a[3]); w.z = cvt_pk_bf16(b[0], b[1]); w.w = cvt_pk_bf16(b[2], b[3]); return w; }
; #define lane lane_id_asm()
; template <int NR> __device__ __forceinline__ void ln_rows(const bf16* (&zr)[NR], bf16* (&ob)[NR], float* (&of)[NR], const float* g, const float* bt, int lane) {
;     ...
;     for (int r = 0; r < NR; ++r) { float s = 0.f;
; #pragma unroll
;         for (int j = 0; j < 4; ++j) s += (v[r][j].x + v[r][j].y) + (v[r][j].z + v[r][j].w);
;         const float mean = wave_sum(s) * (1.f / 1024.f); float s2 = 0.f;
; #pragma unroll
;         for (int j = 0; j < 4; ++j) { v[r][j] = v[r][j] - mean; s2 += (v[r][j].x * v[r][j].x + v[r][j].y * v[r][j].y) + (v[r][j].z * v[r][j].z + v[r][j].w * v[r][j].w); }
;         const float rstd = 1.f / sqrtf(wave_sum(s2) * (1.f / 1024.f) + LN_EPS);
; #pragma unroll
;         for (int j = 0; j < 4; ++j) v[r][j] = v[r][j] * rstd * gg[j] + bb[j];
;         if (ob[r]) { *((v4u*)ob[r] + lane) = epi::pack8(v[r][0], v[r][1]); *((v4u*)ob[r] + 64 + lane) = epi::pack8(v[r][2], v[r][3]); }
	v_add_f32_e32 v44, v44, v45
	ds_bpermute_b32 v45, v117, v44
	s_waitcnt lgkmcnt(0)
	v_add_f32_e32 v44, v44, v45
	ds_bpermute_b32 v45, v116, v44
	s_waitcnt lgkmcnt(0)
	v_add_f32_e32 v57, v44, v45
	v_fmac_f32_e32 v42, 0xba800000, v57
	v_fmac_f32_e32 v43, 0xba800000, v57
	v_fmac_f32_e32 v41, 0xba800000, v57
	v_fmac_f32_e32 v40, 0xba800000, v57
	v_mov_b32_e32 v44, v41
	v_mov_b32_e32 v45, v43
	v_mov_b32_e32 v41, v42
	v_pk_mul_f32 v[46:47], v[44:45], v[44:45]
	v_pk_mul_f32 v[42:43], v[40:41], v[40:41]
	v_fmac_f32_e32 v38, 0xba800000, v57
	v_fmac_f32_e32 v39, 0xba800000, v57
	v_fmac_f32_e32 v37, 0xba800000, v57
	v_pk_mov_b32 v[80:81], v[42:43], v[46:47] op_sel:[1,0]
	v_mov_b32_e32 v43, v47
	v_fmac_f32_e32 v36, 0xba800000, v57
	v_mov_b32_e32 v46, v37
	v_mov_b32_e32 v47, v39
	v_mov_b32_e32 v37, v38
	v_pk_add_f32 v[42:43], v[80:81], v[42:43]
	v_pk_mul_f32 v[80:81], v[46:47], v[46:47]
	v_pk_mul_f32 v[38:39], v[36:37], v[36:37]
	v_fmac_f32_e32 v72, 0xba800000, v57
	v_pk_mov_b32 v[82:83], v[38:39], v[80:81] op_sel:[1,0]
	v_mov_b32_e32 v39, v81
	v_pk_add_f32 v[38:39], v[82:83], v[38:39]
	v_fmac_f32_e32 v73, 0xba800000, v57
	v_pk_add_f32 v[38:39], v[38:39], v[38:39] op_sel_hi:[0,1]
	v_fmac_f32_e32 v74, 0xba800000, v57
	v_mul_f32_e32 v38, v72, v72
	v_fmac_f32_e32 v75, 0xba800000, v57
	v_pk_fma_f32 v[80:81], v[72:73], v[72:73], v[38:39] op_sel_hi:[1,1,0]
	v_mul_f32_e32 v38, v74, v74
	v_pk_add_f32 v[42:43], v[42:43], v[42:43] op_sel_hi:[0,1]
	v_pk_fma_f32 v[82:83], v[74:75], v[74:75], v[38:39] op_sel_hi:[1,1,0]
	v_fmac_f32_e32 v76, 0xba800000, v57
	v_fmac_f32_e32 v68, 0xba800000, v57
	v_fmac_f32_e32 v78, 0xba800000, v57
	v_fmac_f32_e32 v70, 0xba800000, v57
	v_mul_f32_e32 v80, v70, v70
	v_mul_f32_e32 v82, v78, v78
	v_mul_f32_e32 v42, v68, v68
	v_mul_f32_e32 v38, v76, v76
	v_pk_add_f32 v[80:81], v[80:81], v[82:83]
	v_pk_add_f32 v[38:39], v[42:43], v[38:39]
	v_mov_b32_e32 v71, v78
	v_pk_add_f32 v[38:39], v[80:81], v[38:39]
	v_mov_b32_e32 v69, v76
	v_add_f32_e32 v38, v38, v39
	ds_bpermute_b32 v39, v121, v38
	s_waitcnt lgkmcnt(0)
	v_add_f32_e32 v38, v38, v39
	ds_bpermute_b32 v39, v120, v38
	s_waitcnt lgkmcnt(0)
	v_add_f32_e32 v38, v38, v39
	ds_bpermute_b32 v39, v119, v38
	s_waitcnt lgkmcnt(0)
	v_add_f32_e32 v38, v38, v39
	ds_bpermute_b32 v39, v118, v38
	s_waitcnt lgkmcnt(0)
	v_add_f32_e32 v38, v38, v39
	ds_bpermute_b32 v39, v117, v38
	s_waitcnt lgkmcnt(0)
	v_add_f32_e32 v38, v38, v39
	ds_bpermute_b32 v39, v116, v38
	s_waitcnt lgkmcnt(0)
	v_add_f32_e32 v38, v38, v39
	v_fmamk_f32 v38, v38, 0x3a800000, v106
	v_cmp_gt_f32_e32 vcc, s19, v38
	v_mul_f32_e32 v39, 0x4f800000, v38
	s_nop 0
	v_cndmask_b32_e32 v38, v38, v39, vcc
	v_sqrt_f32_e32 v39, v38
	s_nop 0
	v_add_u32_e32 v42, -1, v39
	v_fma_f32 v43, -v42, v39, v38
	v_cmp_ge_f32_e64 s[42:43], 0, v43
	v_add_u32_e32 v43, 1, v39
	s_nop 0
	v_cndmask_b32_e64 v42, v39, v42, s[42:43]
	v_fma_f32 v39, -v43, v39, v38
	v_cmp_lt_f32_e64 s[42:43], 0, v39
	s_nop 1
	v_cndmask_b32_e64 v39, v42, v43, s[42:43]
	v_mul_f32_e32 v42, 0x37800000, v39
	v_cndmask_b32_e32 v39, v39, v42, vcc
	v_cmp_class_f32_e32 vcc, v38, v107
	s_nop 1
	v_cndmask_b32_e32 v38, v39, v38, vcc
	v_div_scale_f32 v39, s[12:13], v38, v38, 1.0
	v_rcp_f32_e32 v42, v39
	s_nop 0
	v_fma_f32 v43, -v39, v42, 1.0
	v_fmac_f32_e32 v42, v43, v42
	v_div_scale_f32 v43, vcc, 1.0, v38, 1.0
	v_mul_f32_e32 v57, v43, v42
	v_fma_f32 v59, -v39, v57, v43
	v_fmac_f32_e32 v57, v59, v42
	v_fma_f32 v39, -v39, v57, v43
	v_div_fmas_f32 v39, v39, v42, v57
	v_div_fixup_f32 v38, v39, v38, 1.0
	v_pk_mul_f32 v[36:37], v[36:37], v[38:39] op_sel_hi:[1,0]
	v_pk_mul_f32 v[40:41], v[40:41], v[38:39] op_sel_hi:[1,0]
	v_pk_mul_f32 v[42:43], v[44:45], v[38:39] op_sel_hi:[1,0]
	v_pk_mul_f32 v[44:45], v[46:47], v[38:39] op_sel_hi:[1,0]
	v_pk_fma_f32 v[46:47], v[8:9], v[36:37], v[16:17]
	v_pk_mul_f32 v[36:37], v[72:73], v[38:39] op_sel_hi:[1,0]
	v_pk_fma_f32 v[40:41], v[24:25], v[40:41], v[28:29]
	v_pk_mul_f32 v[72:73], v[74:75], v[38:39] op_sel_hi:[1,0]
	v_pk_fma_f32 v[74:75], v[12:13], v[36:37], v[20:21]
	v_pk_mul_f32 v[36:37], v[70:71], v[38:39] op_sel_hi:[1,0]
	v_pk_mul_f32 v[38:39], v[68:69], v[38:39] op_sel_hi:[1,0]
	v_pk_fma_f32 v[42:43], v[26:27], v[42:43], v[30:31]
	v_pk_fma_f32 v[44:45], v[10:11], v[44:45], v[18:19]
	v_pk_fma_f32 v[68:69], v[2:3], v[38:39], v[6:7]
	v_pk_fma_f32 v[70:71], v[0:1], v[36:37], v[4:5]
	v_cvt_pk_bf16_f32 v36, v40, v41
	v_cvt_pk_bf16_f32 v37, v42, v43
	v_cvt_pk_bf16_f32 v38, v46, v47
	v_cvt_pk_bf16_f32 v39, v44, v45
	v_lshl_add_u64 v[40:41], v[54:55], 0, s[14:15]
	v_pk_fma_f32 v[72:73], v[14:15], v[72:73], v[22:23]
	global_store_dwordx4 v[40:41], v[36:39], off
	v_add_f32_e32 v59, v62, v63
	v_pk_add_f32 v[42:43], v[58:59], v[64:65]
	v_cvt_pk_bf16_f32 v36, v74, v75
	v_cvt_pk_bf16_f32 v37, v72, v73
	v_cvt_pk_bf16_f32 v38, v70, v71
	v_cvt_pk_bf16_f32 v39, v68, v69
	global_store_dwordx4 v[40:41], v[36:39], off offset:1024
	s_nop 1
	v_lshlrev_b32_e32 v37, 16, v33
	v_lshlrev_b32_e32 v36, 16, v32
	v_and_b32_e32 v39, 0xffff0000, v33
	v_and_b32_e32 v38, 0xffff0000, v32
	v_pk_add_f32 v[32:33], v[36:37], v[38:39]
	s_nop 0
	v_add_f32_e32 v32, v32, v33
	v_add_f32_e32 v61, 0, v32
	v_lshlrev_b32_e32 v33, 16, v35
	v_lshlrev_b32_e32 v32, 16, v34
	v_and_b32_e32 v35, 0xffff0000, v35
	v_and_b32_e32 v34, 0xffff0000, v34
	v_pk_add_f32 v[40:41], v[32:33], v[34:35]
	s_nop 0
	v_pk_add_f32 v[40:41], v[40:41], v[40:41] op_sel_hi:[0,1]
	v_mov_b32_e32 v57, v41
	v_pk_add_f32 v[40:41], v[56:57], v[60:61]
	s_nop 0
	v_pk_add_f32 v[40:41], v[42:43], v[40:41]
	s_nop 0
	v_add_f32_e32 v40, v40, v41
	ds_bpermute_b32 v41, v121, v40
	s_waitcnt lgkmcnt(0)
; __device__ __forceinline__ u32x4 pack8(f32x4 a, f32x4 b) { u32x4 w; w.x = cvt_pk_bf16(a[0], a[1]); w.y = cvt_pk_bf16(a[2], a[3]); w.z = cvt_pk_bf16(b[0], b[1]); w.w = cvt_pk_bf16(b[2], b[3]); return w; }
; #define lane lane_id_asm()
; template <int NR> __device__ __forceinline__ void ln_rows(const bf16* (&zr)[NR], bf16* (&ob)[NR], float* (&of)[NR], const float* g, const float* bt, int lane) {
;     ...
;     for (int r = 0; r < NR; ++r) { float s = 0.f;
; #pragma unroll
;         for (int j = 0; j < 4; ++j) s += (v[r][j].x + v[r][j].y) + (v[r][j].z + v[r][j].w);
;         const float mean = wave_sum(s) * (1.f / 1024.f); float s2 = 0.f;
; #pragma unroll
;         for (int j = 0; j < 4; ++j) { v[r][j] = v[r][j] - mean; s2 += (v[r][j].x * v[r][j].x + v[r][j].y * v[r][j].y) + (v[r][j].z * v[r][j].z + v[r][j].w * v[r][j].w); }
;         const float rstd = 1.f / sqrtf(wave_sum(s2) * (1.f / 1024.f) + LN_EPS);
; #pragma unroll
;         for (int j = 0; j < 4; ++j) v[r][j] = v[r][j] * rstd * gg[j] + bb[j];
;         if (ob[r]) { *((v4u*)ob[r] + lane) = epi::pack8(v[r][0], v[r][1]); *((v4u*)ob[r] + 64 + lane) = epi::pack8(v[r][2], v[r][3]); }
;         if (of[r]) { f32x4* o = (f32x4*)of[r]; __builtin_nontemporal_store(v[r][0], o + 2 * lane); __builtin_nontemporal_store(v[r][1], o + 2 * lane + 1); __builtin_nontemporal_store(v[r][2], o + 128 + 2 * lane); __builtin_nontemporal_store(v[r][3], o + 128 + 2 * lane + 1); } }
; }
	v_add_f32_e32 v40, v40, v41
	ds_bpermute_b32 v41, v120, v40
	s_waitcnt lgkmcnt(0)
	v_add_f32_e32 v40, v40, v41
	ds_bpermute_b32 v41, v119, v40
	s_waitcnt lgkmcnt(0)
	v_add_f32_e32 v40, v40, v41
	ds_bpermute_b32 v41, v118, v40
	s_waitcnt lgkmcnt(0)
	v_add_f32_e32 v40, v40, v41
	ds_bpermute_b32 v41, v117, v40
	s_waitcnt lgkmcnt(0)
	v_add_f32_e32 v40, v40, v41
	ds_bpermute_b32 v41, v116, v40
	s_waitcnt lgkmcnt(0)
	v_add_f32_e32 v57, v40, v41
	v_fmac_f32_e32 v38, 0xba800000, v57
	v_fmac_f32_e32 v39, 0xba800000, v57
	v_fmac_f32_e32 v37, 0xba800000, v57
	v_fmac_f32_e32 v36, 0xba800000, v57
	v_mov_b32_e32 v40, v37
	v_mov_b32_e32 v41, v39
	v_mov_b32_e32 v37, v38
	v_pk_mul_f32 v[42:43], v[40:41], v[40:41]
	v_pk_mul_f32 v[38:39], v[36:37], v[36:37]
	v_fmac_f32_e32 v34, 0xba800000, v57
	v_fmac_f32_e32 v35, 0xba800000, v57
	v_fmac_f32_e32 v33, 0xba800000, v57
	v_pk_mov_b32 v[44:45], v[38:39], v[42:43] op_sel:[1,0]
	v_mov_b32_e32 v39, v43
	v_fmac_f32_e32 v32, 0xba800000, v57
	v_mov_b32_e32 v42, v33
	v_mov_b32_e32 v43, v35
	v_mov_b32_e32 v33, v34
	v_pk_add_f32 v[38:39], v[44:45], v[38:39]
	v_pk_mul_f32 v[44:45], v[42:43], v[42:43]
	v_pk_mul_f32 v[34:35], v[32:33], v[32:33]
	v_fmac_f32_e32 v62, 0xba800000, v57
	v_pk_mov_b32 v[46:47], v[34:35], v[44:45] op_sel:[1,0]
	v_mov_b32_e32 v35, v45
	v_pk_add_f32 v[34:35], v[46:47], v[34:35]
	v_fmac_f32_e32 v63, 0xba800000, v57
	v_pk_add_f32 v[34:35], v[34:35], v[34:35] op_sel_hi:[0,1]
	v_fmac_f32_e32 v66, 0xba800000, v57
	v_mul_f32_e32 v34, v62, v62
	v_fmac_f32_e32 v67, 0xba800000, v57
	v_pk_fma_f32 v[44:45], v[62:63], v[62:63], v[34:35] op_sel_hi:[1,1,0]
	v_mul_f32_e32 v34, v66, v66
	v_pk_add_f32 v[38:39], v[38:39], v[38:39] op_sel_hi:[0,1]
	v_pk_fma_f32 v[46:47], v[66:67], v[66:67], v[34:35] op_sel_hi:[1,1,0]
	v_fmac_f32_e32 v60, 0xba800000, v57
	v_fmac_f32_e32 v56, 0xba800000, v57
	v_fmac_f32_e32 v64, 0xba800000, v57
	v_fmac_f32_e32 v58, 0xba800000, v57
	v_mul_f32_e32 v44, v58, v58
	v_mul_f32_e32 v46, v64, v64
	v_mul_f32_e32 v38, v56, v56
	v_mul_f32_e32 v34, v60, v60
	v_pk_add_f32 v[44:45], v[44:45], v[46:47]
	v_pk_add_f32 v[34:35], v[38:39], v[34:35]
	v_mov_b32_e32 v59, v64
	v_pk_add_f32 v[34:35], v[44:45], v[34:35]
	v_mov_b32_e32 v57, v60
	v_add_f32_e32 v34, v34, v35
	ds_bpermute_b32 v35, v121, v34
	s_waitcnt lgkmcnt(0)
	v_add_f32_e32 v34, v34, v35
	ds_bpermute_b32 v35, v120, v34
	s_waitcnt lgkmcnt(0)
	v_add_f32_e32 v34, v34, v35
	ds_bpermute_b32 v35, v119, v34
	s_waitcnt lgkmcnt(0)
	v_add_f32_e32 v34, v34, v35
	ds_bpermute_b32 v35, v118, v34
	s_waitcnt lgkmcnt(0)
	v_add_f32_e32 v34, v34, v35
	ds_bpermute_b32 v35, v117, v34
	s_waitcnt lgkmcnt(0)
	v_add_f32_e32 v34, v34, v35
	ds_bpermute_b32 v35, v116, v34
	s_waitcnt lgkmcnt(0)
	v_add_f32_e32 v34, v34, v35
	v_fmamk_f32 v34, v34, 0x3a800000, v106
	v_cmp_gt_f32_e32 vcc, s19, v34
	v_mul_f32_e32 v35, 0x4f800000, v34
	s_nop 0
	v_cndmask_b32_e32 v34, v34, v35, vcc
	v_sqrt_f32_e32 v35, v34
	s_nop 0
	v_add_u32_e32 v38, -1, v35
	v_fma_f32 v39, -v38, v35, v34
	v_cmp_ge_f32_e64 s[42:43], 0, v39
	v_add_u32_e32 v39, 1, v35
	s_nop 0
	v_cndmask_b32_e64 v38, v35, v38, s[42:43]
	v_fma_f32 v35, -v39, v35, v34
	v_cmp_lt_f32_e64 s[42:43], 0, v35
	s_nop 1
	v_cndmask_b32_e64 v35, v38, v39, s[42:43]
	v_mul_f32_e32 v38, 0x37800000, v35
	v_cndmask_b32_e32 v35, v35, v38, vcc
	v_cmp_class_f32_e32 vcc, v34, v107
	s_nop 1
	v_cndmask_b32_e32 v34, v35, v34, vcc
	v_div_scale_f32 v35, s[12:13], v34, v34, 1.0
	v_rcp_f32_e32 v38, v35
	s_nop 0
	v_fma_f32 v39, -v35, v38, 1.0
	v_fmac_f32_e32 v38, v39, v38
	v_div_scale_f32 v39, vcc, 1.0, v34, 1.0
	v_mul_f32_e32 v44, v39, v38
	v_fma_f32 v45, -v35, v44, v39
	v_fmac_f32_e32 v44, v45, v38
	v_fma_f32 v35, -v35, v44, v39
	v_div_fmas_f32 v35, v35, v38, v44
	v_div_fixup_f32 v34, v35, v34, 1.0
	v_pk_mul_f32 v[36:37], v[36:37], v[34:35] op_sel_hi:[1,0]
	v_pk_mul_f32 v[38:39], v[40:41], v[34:35] op_sel_hi:[1,0]
	v_pk_fma_f32 v[24:25], v[24:25], v[36:37], v[28:29]
	v_pk_fma_f32 v[26:27], v[26:27], v[38:39], v[30:31]
	v_pk_mul_f32 v[28:29], v[32:33], v[34:35] op_sel_hi:[1,0]
	v_pk_mul_f32 v[30:31], v[42:43], v[34:35] op_sel_hi:[1,0]
	v_pk_fma_f32 v[8:9], v[8:9], v[28:29], v[16:17]
	v_pk_fma_f32 v[10:11], v[10:11], v[30:31], v[18:19]
	v_pk_mul_f32 v[16:17], v[62:63], v[34:35] op_sel_hi:[1,0]
	v_pk_mul_f32 v[18:19], v[66:67], v[34:35] op_sel_hi:[1,0]
	v_pk_fma_f32 v[12:13], v[12:13], v[16:17], v[20:21]
	v_pk_fma_f32 v[14:15], v[14:15], v[18:19], v[22:23]
	v_pk_mul_f32 v[16:17], v[58:59], v[34:35] op_sel_hi:[1,0]
	v_pk_mul_f32 v[18:19], v[56:57], v[34:35] op_sel_hi:[1,0]
	v_pk_fma_f32 v[4:5], v[0:1], v[16:17], v[4:5]
	v_pk_fma_f32 v[6:7], v[2:3], v[18:19], v[6:7]
	v_cvt_pk_bf16_f32 v0, v24, v25
	v_cvt_pk_bf16_f32 v1, v26, v27
	v_cvt_pk_bf16_f32 v2, v8, v9
	v_cvt_pk_bf16_f32 v3, v10, v11
	v_lshl_add_u64 v[8:9], v[54:55], 0, s[4:5]
	global_store_dwordx4 v[8:9], v[0:3], off
	s_nop 1
	v_cvt_pk_bf16_f32 v0, v12, v13
	v_cvt_pk_bf16_f32 v1, v14, v15
	v_cvt_pk_bf16_f32 v2, v4, v5
	v_cvt_pk_bf16_f32 v3, v6, v7
	global_store_dwordx4 v[8:9], v[0:3], off offset:1024
	s_branch .LBB0_1062

; __device__ __forceinline__ void unpack8(u32x4 w, f32x4& a, f32x4& b) { a = (f32x4){bflo(w.x), bfhi(w.x), bflo(w.y), bfhi(w.y)}; b = (f32x4){bflo(w.z), bfhi(w.z), bflo(w.w), bfhi(w.w)}; }
; #define lane lane_id_asm()
; template <int NR> __device__ __forceinline__ void ln_rows(const bf16* (&zr)[NR], bf16* (&ob)[NR], float* (&of)[NR], const float* g, const float* bt, int lane) {
;     f32x4 v[NR][4];
; #pragma unroll
;     for (int r = 0; r < NR; ++r) { const v4u w0 = __builtin_nontemporal_load((const v4u*)zr[r] + lane), w1 = __builtin_nontemporal_load((const v4u*)zr[r] + 64 + lane); epi::unpack8(w0, v[r][0], v[r][1]); epi::unpack8(w1, v[r][2], v[r][3]); }
;     f32x4 gg[4], bb[4];
; #pragma unroll
;     for (int j = 0; j < 4; ++j) { gg[j] = *((const f32x4*)g + (j >> 1) * 128 + 2 * lane + (j & 1)); bb[j] = *((const f32x4*)bt + (j >> 1) * 128 + 2 * lane + (j & 1)); }
; #pragma unroll
;     for (int r = 0; r < NR; ++r) { float s = 0.f;
; #pragma unroll
;         for (int j = 0; j < 4; ++j) s += (v[r][j].x + v[r][j].y) + (v[r][j].z + v[r][j].w);
;         const float mean = wave_sum(s) * (1.f / 1024.f); float s2 = 0.f;
; #pragma unroll
;         for (int j = 0; j < 4; ++j) { v[r][j] = v[r][j] - mean; s2 += (v[r][j].x * v[r][j].x + v[r][j].y * v[r][j].y) + (v[r][j].z * v[r][j].z + v[r][j].w * v[r][j].w); }
;         const float rstd = 1.f / sqrtf(wave_sum(s2) * (1.f / 1024.f) + LN_EPS);
.LBB0_1402:
	s_ashr_i32 s9, s8, 31
	s_lshl_b64 s[46:47], s[8:9], 11
	v_lshl_add_u64 v[0:1], v[52:53], 0, s[46:47]
	global_load_dwordx4 v[44:47], v[0:1], off nt
	s_nop 0
	global_load_dwordx4 v[0:3], v[0:1], off offset:1024 nt
	s_sub_i32 s12, s4, s62
	s_ashr_i32 s13, s12, 31
	s_lshl_b64 s[44:45], s[12:13], 11
	s_add_i32 s14, s12, s33
	s_ashr_i32 s15, s14, 31
	s_lshl_b64 s[14:15], s[14:15], 11
	s_ashr_i32 s5, s4, 31
	s_lshl_b64 s[4:5], s[4:5], 11
	v_lshl_add_u64 v[212:213], v[52:53], 0, s[44:45]
	global_load_dwordx4 v[40:43], v[212:213], off nt
	global_load_dwordx4 v[200:203], v[212:213], off offset:1024 nt
	v_lshl_add_u64 v[212:213], v[52:53], 0, s[14:15]
	global_load_dwordx4 v[36:39], v[212:213], off nt
	global_load_dwordx4 v[204:207], v[212:213], off offset:1024 nt
	v_lshl_add_u64 v[212:213], v[52:53], 0, s[4:5]
	global_load_dwordx4 v[32:35], v[212:213], off nt
	global_load_dwordx4 v[208:211], v[212:213], off offset:1024 nt
	v_cmp_lt_i32_e32 vcc, v110, v109
	s_waitcnt vmcnt(6)
	v_lshlrev_b32_e32 v105, 16, v45
	v_lshlrev_b32_e32 v96, 16, v0
	v_and_b32_e32 v97, 0xffff0000, v0
	v_lshlrev_b32_e32 v98, 16, v1
	v_and_b32_e32 v99, 0xffff0000, v1
	v_lshlrev_b32_e32 v94, 16, v2
	v_and_b32_e32 v102, 0xffff0000, v2
	v_lshlrev_b32_e32 v92, 16, v3
	v_and_b32_e32 v100, 0xffff0000, v3
	v_lshlrev_b32_e32 v104, 16, v44
	v_and_b32_e32 v123, 0xffff0000, v45
	v_and_b32_e32 v122, 0xffff0000, v44
	v_pk_add_f32 v[44:45], v[104:105], v[122:123]
	v_and_b32_e32 v125, 0xffff0000, v47
	v_add_f32_e32 v44, v44, v45
	v_add_f32_e32 v101, 0, v44
	v_lshlrev_b32_e32 v45, 16, v47
	v_lshlrev_b32_e32 v44, 16, v46
	v_and_b32_e32 v124, 0xffff0000, v46
	v_pk_add_f32 v[46:47], v[44:45], v[124:125]
	v_add_f32_e32 v95, v96, v97
	v_pk_add_f32 v[46:47], v[46:47], v[46:47] op_sel_hi:[0,1]
	v_add_f32_e32 v103, v98, v99
	v_mov_b32_e32 v93, v47
	v_pk_add_f32 v[126:127], v[94:95], v[102:103]
	v_pk_add_f32 v[46:47], v[92:93], v[100:101]
	v_cndmask_b32_e32 v57, v108, v110, vcc
	v_pk_add_f32 v[46:47], v[126:127], v[46:47]
	v_lshlrev_b32_e32 v121, 2, v57
	v_add_f32_e32 v46, v46, v47
	ds_bpermute_b32 v47, v121, v46
	v_cmp_lt_i32_e32 vcc, v111, v109
	s_waitcnt lgkmcnt(0)
	v_add_f32_e32 v46, v46, v47
	v_cndmask_b32_e32 v57, v108, v111, vcc
	v_lshlrev_b32_e32 v120, 2, v57
	ds_bpermute_b32 v47, v120, v46
	v_cmp_lt_i32_e32 vcc, v112, v109
	s_waitcnt lgkmcnt(0)
	v_add_f32_e32 v46, v46, v47
	v_cndmask_b32_e32 v57, v108, v112, vcc
	v_lshlrev_b32_e32 v119, 2, v57
	ds_bpermute_b32 v47, v119, v46
	v_cmp_lt_i32_e32 vcc, v113, v109
	s_waitcnt lgkmcnt(0)
	v_add_f32_e32 v46, v46, v47
	v_cndmask_b32_e32 v57, v108, v113, vcc
	v_lshlrev_b32_e32 v118, 2, v57
	ds_bpermute_b32 v47, v118, v46
	v_cmp_lt_i32_e32 vcc, v114, v109
	s_waitcnt lgkmcnt(0)
	v_add_f32_e32 v46, v46, v47
	v_cndmask_b32_e32 v57, v108, v114, vcc
	v_lshlrev_b32_e32 v117, 2, v57
	ds_bpermute_b32 v47, v117, v46
	v_cmp_lt_i32_e32 vcc, v115, v109
	s_waitcnt lgkmcnt(0)
	v_add_f32_e32 v46, v46, v47
	v_cndmask_b32_e32 v57, v108, v115, vcc
	v_lshlrev_b32_e32 v116, 2, v57
	ds_bpermute_b32 v47, v116, v46
	s_waitcnt lgkmcnt(0)
	v_add_f32_e32 v57, v46, v47
	v_fmac_f32_e32 v122, 0xba800000, v57
	v_fmac_f32_e32 v123, 0xba800000, v57
	v_fmac_f32_e32 v105, 0xba800000, v57
	v_fmac_f32_e32 v104, 0xba800000, v57
	v_mov_b32_e32 v46, v105
	v_mov_b32_e32 v47, v123
	v_mov_b32_e32 v105, v122
	v_pk_mul_f32 v[126:127], v[46:47], v[46:47]
	v_pk_mul_f32 v[122:123], v[104:105], v[104:105]
	v_fmac_f32_e32 v124, 0xba800000, v57
	v_pk_mov_b32 v[128:129], v[122:123], v[126:127] op_sel:[1,0]
	v_mov_b32_e32 v123, v127
	s_waitcnt vmcnt(4)
	v_lshlrev_b32_e32 v84, 16, v200
	v_and_b32_e32 v85, 0xffff0000, v200
	v_lshlrev_b32_e32 v86, 16, v201
	v_and_b32_e32 v87, 0xffff0000, v201
	v_lshlrev_b32_e32 v82, 16, v202
	v_and_b32_e32 v90, 0xffff0000, v202
	v_lshlrev_b32_e32 v80, 16, v203
	v_and_b32_e32 v88, 0xffff0000, v203
	v_fmac_f32_e32 v125, 0xba800000, v57
	v_fmac_f32_e32 v45, 0xba800000, v57
	v_pk_add_f32 v[122:123], v[128:129], v[122:123]
	v_fmac_f32_e32 v44, 0xba800000, v57
	v_mov_b32_e32 v126, v45
	v_mov_b32_e32 v127, v125
	v_mov_b32_e32 v45, v124
	v_pk_add_f32 v[122:123], v[122:123], v[122:123] op_sel_hi:[0,1]
	v_pk_mul_f32 v[128:129], v[126:127], v[126:127]
	v_pk_mul_f32 v[124:125], v[44:45], v[44:45]
	v_fmac_f32_e32 v96, 0xba800000, v57
	v_pk_mov_b32 v[130:131], v[124:125], v[128:129] op_sel:[1,0]
	v_mov_b32_e32 v125, v129
	v_fmac_f32_e32 v97, 0xba800000, v57
	v_fmac_f32_e32 v98, 0xba800000, v57
	v_mul_f32_e32 v122, v96, v96
	v_pk_add_f32 v[124:125], v[130:131], v[124:125]
	v_fmac_f32_e32 v99, 0xba800000, v57
	v_pk_fma_f32 v[128:129], v[96:97], v[96:97], v[122:123] op_sel_hi:[1,1,0]
	v_mul_f32_e32 v122, v98, v98
	v_pk_add_f32 v[124:125], v[124:125], v[124:125] op_sel_hi:[0,1]
	v_pk_fma_f32 v[130:131], v[98:99], v[98:99], v[122:123] op_sel_hi:[1,1,0]
	v_fmac_f32_e32 v100, 0xba800000, v57
	v_fmac_f32_e32 v92, 0xba800000, v57
	v_fmac_f32_e32 v102, 0xba800000, v57
	v_fmac_f32_e32 v94, 0xba800000, v57
	v_mul_f32_e32 v128, v94, v94
	v_mul_f32_e32 v130, v102, v102
	v_mul_f32_e32 v122, v92, v92
	v_mul_f32_e32 v124, v100, v100
	v_pk_add_f32 v[128:129], v[128:129], v[130:131]
	v_pk_add_f32 v[122:123], v[122:123], v[124:125]
	v_mov_b32_e32 v95, v102
	v_pk_add_f32 v[122:123], v[128:129], v[122:123]
	v_mov_b32_e32 v93, v100
	v_add_f32_e32 v57, v122, v123
	ds_bpermute_b32 v59, v121, v57
	v_lshl_add_u64 v[100:101], v[54:55], 0, s[46:47]
	v_add_f32_e32 v83, v84, v85
	v_add_f32_e32 v91, v86, v87
	s_waitcnt lgkmcnt(0)
	v_add_f32_e32 v57, v57, v59
	ds_bpermute_b32 v59, v120, v57
	s_waitcnt lgkmcnt(0)
	v_add_f32_e32 v57, v57, v59
	ds_bpermute_b32 v59, v119, v57
	s_waitcnt lgkmcnt(0)
; __device__ __forceinline__ u32x4 pack8(f32x4 a, f32x4 b) { u32x4 w; w.x = cvt_pk_bf16(a[0], a[1]); w.y = cvt_pk_bf16(a[2], a[3]); w.z = cvt_pk_bf16(b[0], b[1]); w.w = cvt_pk_bf16(b[2], b[3]); return w; }
; #define lane lane_id_asm()
; template <int NR> __device__ __forceinline__ void ln_rows(const bf16* (&zr)[NR], bf16* (&ob)[NR], float* (&of)[NR], const float* g, const float* bt, int lane) {
;     ...
;     for (int r = 0; r < NR; ++r) { float s = 0.f;
; #pragma unroll
;         for (int j = 0; j < 4; ++j) s += (v[r][j].x + v[r][j].y) + (v[r][j].z + v[r][j].w);
;         const float mean = wave_sum(s) * (1.f / 1024.f); float s2 = 0.f;
; #pragma unroll
;         for (int j = 0; j < 4; ++j) { v[r][j] = v[r][j] - mean; s2 += (v[r][j].x * v[r][j].x + v[r][j].y * v[r][j].y) + (v[r][j].z * v[r][j].z + v[r][j].w * v[r][j].w); }
;         const float rstd = 1.f / sqrtf(wave_sum(s2) * (1.f / 1024.f) + LN_EPS);
; #pragma unroll
;         for (int j = 0; j < 4; ++j) v[r][j] = v[r][j] * rstd * gg[j] + bb[j];
;         if (ob[r]) { *((v4u*)ob[r] + lane) = epi::pack8(v[r][0], v[r][1]); *((v4u*)ob[r] + 64 + lane) = epi::pack8(v[r][2], v[r][3]); }
	v_add_f32_e32 v57, v57, v59
	ds_bpermute_b32 v59, v118, v57
	s_waitcnt lgkmcnt(0)
	v_add_f32_e32 v57, v57, v59
	ds_bpermute_b32 v59, v117, v57
	s_waitcnt lgkmcnt(0)
	v_add_f32_e32 v57, v57, v59
	ds_bpermute_b32 v59, v116, v57
	s_waitcnt lgkmcnt(0)
	v_add_f32_e32 v57, v57, v59
	v_fmamk_f32 v57, v57, 0x3a800000, v106
	v_cmp_gt_f32_e32 vcc, s18, v57
	v_mul_f32_e32 v59, 0x4f800000, v57
	s_waitcnt vmcnt(2)
	v_lshlrev_b32_e32 v72, 16, v204
	v_and_b32_e32 v73, 0xffff0000, v204
	v_lshlrev_b32_e32 v74, 16, v205
	v_and_b32_e32 v75, 0xffff0000, v205
	v_lshlrev_b32_e32 v70, 16, v206
	v_and_b32_e32 v78, 0xffff0000, v206
	v_lshlrev_b32_e32 v68, 16, v207
	v_and_b32_e32 v76, 0xffff0000, v207
	v_cndmask_b32_e32 v57, v57, v59, vcc
	v_sqrt_f32_e32 v59, v57
	v_add_f32_e32 v79, v74, v75
	v_add_u32_e32 v61, -1, v59
	v_fma_f32 v65, -v61, v59, v57
	v_cmp_ge_f32_e64 s[42:43], 0, v65
	v_add_u32_e32 v65, 1, v59
	s_waitcnt vmcnt(0)
	v_lshlrev_b32_e32 v62, 16, v208
	v_and_b32_e32 v63, 0xffff0000, v208
	v_lshlrev_b32_e32 v66, 16, v209
	v_and_b32_e32 v67, 0xffff0000, v209
	v_lshlrev_b32_e32 v58, 16, v210
	v_and_b32_e32 v64, 0xffff0000, v210
	v_lshlrev_b32_e32 v56, 16, v211
	v_and_b32_e32 v60, 0xffff0000, v211
	global_load_dwordx4 v[8:11], v[48:49], off offset:16
	global_load_dwordx4 v[24:27], v[48:49], off
	global_load_dwordx4 v[16:19], v[50:51], off offset:16
	global_load_dwordx4 v[28:31], v[50:51], off
	global_load_dwordx4 v[0:3], v[48:49], off offset:2064
	global_load_dwordx4 v[12:15], v[48:49], off offset:2048
	global_load_dwordx4 v[4:7], v[50:51], off offset:2064
	global_load_dwordx4 v[20:23], v[50:51], off offset:2048
	v_cndmask_b32_e64 v61, v59, v61, s[42:43]
	v_fma_f32 v59, -v65, v59, v57
	v_cmp_lt_f32_e64 s[42:43], 0, v59
	s_nop 1
	v_cndmask_b32_e64 v59, v61, v65, s[42:43]
	v_mul_f32_e32 v61, 0x37800000, v59
	v_cndmask_b32_e32 v59, v59, v61, vcc
	v_cmp_class_f32_e32 vcc, v57, v107
	s_nop 1
	v_cndmask_b32_e32 v57, v59, v57, vcc
	v_div_scale_f32 v59, s[12:13], v57, v57, 1.0
	v_rcp_f32_e32 v61, v59
	s_nop 0
	v_fma_f32 v65, -v59, v61, 1.0
	v_fmac_f32_e32 v61, v65, v61
	v_div_scale_f32 v65, vcc, 1.0, v57, 1.0
	v_mul_f32_e32 v69, v65, v61
	v_fma_f32 v71, -v59, v69, v65
	v_fmac_f32_e32 v69, v71, v61
	v_fma_f32 v59, -v59, v69, v65
	v_div_fmas_f32 v59, v59, v61, v69
	v_div_fixup_f32 v122, v59, v57, 1.0
	v_pk_mul_f32 v[44:45], v[44:45], v[122:123] op_sel_hi:[1,0]
	v_pk_mul_f32 v[46:47], v[46:47], v[122:123] op_sel_hi:[1,0]
	v_pk_mul_f32 v[124:125], v[126:127], v[122:123] op_sel_hi:[1,0]
	v_pk_mul_f32 v[104:105], v[104:105], v[122:123] op_sel_hi:[1,0]
	v_pk_mul_f32 v[92:93], v[92:93], v[122:123] op_sel_hi:[1,0]
	v_add_f32_e32 v71, v72, v73
	v_add_f32_e32 v65, v66, v67
	s_waitcnt vmcnt(5)
	v_pk_fma_f32 v[126:127], v[8:9], v[44:45], v[16:17]
	v_pk_mul_f32 v[44:45], v[96:97], v[122:123] op_sel_hi:[1,0]
	s_waitcnt vmcnt(4)
	v_pk_fma_f32 v[46:47], v[26:27], v[46:47], v[30:31]
	v_pk_mul_f32 v[96:97], v[98:99], v[122:123] op_sel_hi:[1,0]
	v_pk_fma_f32 v[104:105], v[24:25], v[104:105], v[28:29]
	s_waitcnt vmcnt(0)
	v_pk_fma_f32 v[98:99], v[12:13], v[44:45], v[20:21]
	v_pk_mul_f32 v[44:45], v[94:95], v[122:123] op_sel_hi:[1,0]
	v_pk_fma_f32 v[124:125], v[10:11], v[124:125], v[18:19]
	v_pk_fma_f32 v[94:95], v[0:1], v[44:45], v[4:5]
	v_cvt_pk_bf16_f32 v44, v104, v105
	v_cvt_pk_bf16_f32 v45, v46, v47
	v_cvt_pk_bf16_f32 v46, v126, v127
	v_cvt_pk_bf16_f32 v47, v124, v125
	v_pk_fma_f32 v[96:97], v[14:15], v[96:97], v[22:23]
	v_pk_fma_f32 v[92:93], v[2:3], v[92:93], v[6:7]
	global_store_dwordx4 v[100:101], v[44:47], off
	s_nop 1
	v_cvt_pk_bf16_f32 v44, v98, v99
	v_cvt_pk_bf16_f32 v45, v96, v97
	v_cvt_pk_bf16_f32 v46, v94, v95
	v_cvt_pk_bf16_f32 v47, v92, v93
	global_store_dwordx4 v[100:101], v[44:47], off offset:1024
	v_pk_add_f32 v[94:95], v[82:83], v[90:91]
	s_nop 0
	v_lshlrev_b32_e32 v45, 16, v41
	v_lshlrev_b32_e32 v44, 16, v40
	v_and_b32_e32 v47, 0xffff0000, v41
	v_and_b32_e32 v46, 0xffff0000, v40
	v_pk_add_f32 v[40:41], v[44:45], v[46:47]
	s_nop 0
	v_add_f32_e32 v40, v40, v41
	v_add_f32_e32 v89, 0, v40
	v_lshlrev_b32_e32 v41, 16, v43
	v_lshlrev_b32_e32 v40, 16, v42
	v_and_b32_e32 v43, 0xffff0000, v43
	v_and_b32_e32 v42, 0xffff0000, v42
	v_pk_add_f32 v[92:93], v[40:41], v[42:43]
	s_nop 0
	v_pk_add_f32 v[92:93], v[92:93], v[92:93] op_sel_hi:[0,1]
	v_mov_b32_e32 v81, v93
	v_pk_add_f32 v[92:93], v[80:81], v[88:89]
	s_nop 0
	v_pk_add_f32 v[92:93], v[94:95], v[92:93]
	s_nop 0
	v_add_f32_e32 v57, v92, v93
	ds_bpermute_b32 v59, v121, v57
	s_waitcnt lgkmcnt(0)
	v_add_f32_e32 v57, v57, v59
	ds_bpermute_b32 v59, v120, v57
	s_waitcnt lgkmcnt(0)
	v_add_f32_e32 v57, v57, v59
	ds_bpermute_b32 v59, v119, v57
	s_waitcnt lgkmcnt(0)
	v_add_f32_e32 v57, v57, v59
	ds_bpermute_b32 v59, v118, v57
	s_waitcnt lgkmcnt(0)
	v_add_f32_e32 v57, v57, v59
	ds_bpermute_b32 v59, v117, v57
	s_waitcnt lgkmcnt(0)
	v_add_f32_e32 v57, v57, v59
	ds_bpermute_b32 v59, v116, v57
	s_waitcnt lgkmcnt(0)
; __device__ __forceinline__ u32x4 pack8(f32x4 a, f32x4 b) { u32x4 w; w.x = cvt_pk_bf16(a[0], a[1]); w.y = cvt_pk_bf16(a[2], a[3]); w.z = cvt_pk_bf16(b[0], b[1]); w.w = cvt_pk_bf16(b[2], b[3]); return w; }
; #define lane lane_id_asm()
; template <int NR> __device__ __forceinline__ void ln_rows(const bf16* (&zr)[NR], bf16* (&ob)[NR], float* (&of)[NR], const float* g, const float* bt, int lane) {
;     ...
;     for (int r = 0; r < NR; ++r) { float s = 0.f;
; #pragma unroll
;         for (int j = 0; j < 4; ++j) s += (v[r][j].x + v[r][j].y) + (v[r][j].z + v[r][j].w);
;         const float mean = wave_sum(s) * (1.f / 1024.f); float s2 = 0.f;
; #pragma unroll
;         for (int j = 0; j < 4; ++j) { v[r][j] = v[r][j] - mean; s2 += (v[r][j].x * v[r][j].x + v[r][j].y * v[r][j].y) + (v[r][j].z * v[r][j].z + v[r][j].w * v[r][j].w); }
;         const float rstd = 1.f / sqrtf(wave_sum(s2) * (1.f / 1024.f) + LN_EPS);
; #pragma unroll
;         for (int j = 0; j < 4; ++j) v[r][j] = v[r][j] * rstd * gg[j] + bb[j];
;         if (ob[r]) { *((v4u*)ob[r] + lane) = epi::pack8(v[r][0], v[r][1]); *((v4u*)ob[r] + 64 + lane) = epi::pack8(v[r][2], v[r][3]); }
	v_add_f32_e32 v57, v57, v59
	v_fmac_f32_e32 v46, 0xba800000, v57
	v_fmac_f32_e32 v47, 0xba800000, v57
	v_fmac_f32_e32 v45, 0xba800000, v57
	v_fmac_f32_e32 v44, 0xba800000, v57
	v_mov_b32_e32 v92, v45
	v_mov_b32_e32 v93, v47
	v_mov_b32_e32 v45, v46
	v_pk_mul_f32 v[94:95], v[92:93], v[92:93]
	v_pk_mul_f32 v[46:47], v[44:45], v[44:45]
	v_fmac_f32_e32 v42, 0xba800000, v57
	v_fmac_f32_e32 v43, 0xba800000, v57
	v_fmac_f32_e32 v41, 0xba800000, v57
	v_pk_mov_b32 v[96:97], v[46:47], v[94:95] op_sel:[1,0]
	v_mov_b32_e32 v47, v95
	v_fmac_f32_e32 v40, 0xba800000, v57
	v_mov_b32_e32 v94, v41
	v_mov_b32_e32 v95, v43
	v_mov_b32_e32 v41, v42
	v_pk_add_f32 v[46:47], v[96:97], v[46:47]
	v_pk_mul_f32 v[96:97], v[94:95], v[94:95]
	v_pk_mul_f32 v[42:43], v[40:41], v[40:41]
	v_fmac_f32_e32 v84, 0xba800000, v57
	v_pk_mov_b32 v[98:99], v[42:43], v[96:97] op_sel:[1,0]
	v_mov_b32_e32 v43, v97
	v_pk_add_f32 v[42:43], v[98:99], v[42:43]
	v_fmac_f32_e32 v85, 0xba800000, v57
	v_pk_add_f32 v[42:43], v[42:43], v[42:43] op_sel_hi:[0,1]
	v_fmac_f32_e32 v86, 0xba800000, v57
	v_mul_f32_e32 v42, v84, v84
	v_fmac_f32_e32 v87, 0xba800000, v57
	v_pk_fma_f32 v[96:97], v[84:85], v[84:85], v[42:43] op_sel_hi:[1,1,0]
	v_mul_f32_e32 v42, v86, v86
	v_pk_add_f32 v[46:47], v[46:47], v[46:47] op_sel_hi:[0,1]
	v_pk_fma_f32 v[98:99], v[86:87], v[86:87], v[42:43] op_sel_hi:[1,1,0]
	v_fmac_f32_e32 v88, 0xba800000, v57
	v_fmac_f32_e32 v80, 0xba800000, v57
	v_fmac_f32_e32 v90, 0xba800000, v57
	v_fmac_f32_e32 v82, 0xba800000, v57
	v_mul_f32_e32 v96, v82, v82
	v_mul_f32_e32 v98, v90, v90
	v_mul_f32_e32 v46, v80, v80
	v_mul_f32_e32 v42, v88, v88
	v_pk_add_f32 v[96:97], v[96:97], v[98:99]
	v_pk_add_f32 v[42:43], v[46:47], v[42:43]
	v_mov_b32_e32 v83, v90
	v_pk_add_f32 v[42:43], v[96:97], v[42:43]
	v_mov_b32_e32 v81, v88
	v_add_f32_e32 v42, v42, v43
	ds_bpermute_b32 v43, v121, v42
	s_waitcnt lgkmcnt(0)
	v_add_f32_e32 v42, v42, v43
	ds_bpermute_b32 v43, v120, v42
	s_waitcnt lgkmcnt(0)
	v_add_f32_e32 v42, v42, v43
	ds_bpermute_b32 v43, v119, v42
	s_waitcnt lgkmcnt(0)
	v_add_f32_e32 v42, v42, v43
	ds_bpermute_b32 v43, v118, v42
	s_waitcnt lgkmcnt(0)
	v_add_f32_e32 v42, v42, v43
	ds_bpermute_b32 v43, v117, v42
	s_waitcnt lgkmcnt(0)
	v_add_f32_e32 v42, v42, v43
	ds_bpermute_b32 v43, v116, v42
	s_waitcnt lgkmcnt(0)
	v_add_f32_e32 v42, v42, v43
	v_fmamk_f32 v42, v42, 0x3a800000, v106
	v_cmp_gt_f32_e32 vcc, s18, v42
	v_mul_f32_e32 v43, 0x4f800000, v42
	s_nop 0
	v_cndmask_b32_e32 v42, v42, v43, vcc
	v_sqrt_f32_e32 v43, v42
	s_nop 0
	v_add_u32_e32 v46, -1, v43
	v_fma_f32 v47, -v46, v43, v42
	v_cmp_ge_f32_e64 s[42:43], 0, v47
	v_add_u32_e32 v47, 1, v43
	s_nop 0
	v_cndmask_b32_e64 v46, v43, v46, s[42:43]
	v_fma_f32 v43, -v47, v43, v42
	v_cmp_lt_f32_e64 s[42:43], 0, v43
	s_nop 1
	v_cndmask_b32_e64 v43, v46, v47, s[42:43]
	v_mul_f32_e32 v46, 0x37800000, v43
	v_cndmask_b32_e32 v43, v43, v46, vcc
	v_cmp_class_f32_e32 vcc, v42, v107
	s_nop 1
	v_cndmask_b32_e32 v42, v43, v42, vcc
	v_div_scale_f32 v43, s[12:13], v42, v42, 1.0
	v_rcp_f32_e32 v46, v43
	s_nop 0
	v_fma_f32 v47, -v43, v46, 1.0
	v_fmac_f32_e32 v46, v47, v46
	v_div_scale_f32 v47, vcc, 1.0, v42, 1.0
	v_mul_f32_e32 v57, v47, v46
	v_fma_f32 v59, -v43, v57, v47
	v_fmac_f32_e32 v57, v59, v46
	v_fma_f32 v43, -v43, v57, v47
	v_div_fmas_f32 v43, v43, v46, v57
	v_div_fixup_f32 v42, v43, v42, 1.0
	v_pk_mul_f32 v[40:41], v[40:41], v[42:43] op_sel_hi:[1,0]
	v_pk_mul_f32 v[44:45], v[44:45], v[42:43] op_sel_hi:[1,0]
	v_pk_mul_f32 v[46:47], v[92:93], v[42:43] op_sel_hi:[1,0]
	v_pk_mul_f32 v[92:93], v[94:95], v[42:43] op_sel_hi:[1,0]
	v_pk_fma_f32 v[94:95], v[8:9], v[40:41], v[16:17]
	v_pk_mul_f32 v[40:41], v[84:85], v[42:43] op_sel_hi:[1,0]
	v_pk_fma_f32 v[44:45], v[24:25], v[44:45], v[28:29]
	v_pk_mul_f32 v[84:85], v[86:87], v[42:43] op_sel_hi:[1,0]
	v_pk_fma_f32 v[86:87], v[12:13], v[40:41], v[20:21]
	v_pk_mul_f32 v[40:41], v[82:83], v[42:43] op_sel_hi:[1,0]
	v_pk_mul_f32 v[42:43], v[80:81], v[42:43] op_sel_hi:[1,0]
	v_pk_fma_f32 v[46:47], v[26:27], v[46:47], v[30:31]
	v_pk_fma_f32 v[92:93], v[10:11], v[92:93], v[18:19]
	v_pk_fma_f32 v[80:81], v[2:3], v[42:43], v[6:7]
	v_pk_fma_f32 v[82:83], v[0:1], v[40:41], v[4:5]
	v_cvt_pk_bf16_f32 v40, v44, v45
	v_cvt_pk_bf16_f32 v41, v46, v47
	v_cvt_pk_bf16_f32 v42, v94, v95
	v_cvt_pk_bf16_f32 v43, v92, v93
	v_lshl_add_u64 v[44:45], v[54:55], 0, s[44:45]
	v_pk_fma_f32 v[84:85], v[14:15], v[84:85], v[22:23]
	global_store_dwordx4 v[44:45], v[40:43], off
	v_pk_add_f32 v[46:47], v[70:71], v[78:79]
	s_nop 0
	v_cvt_pk_bf16_f32 v40, v86, v87
	v_cvt_pk_bf16_f32 v41, v84, v85
	v_cvt_pk_bf16_f32 v42, v82, v83
	v_cvt_pk_bf16_f32 v43, v80, v81
	global_store_dwordx4 v[44:45], v[40:43], off offset:1024
	s_nop 1
	v_lshlrev_b32_e32 v41, 16, v37
	v_lshlrev_b32_e32 v40, 16, v36
	v_and_b32_e32 v43, 0xffff0000, v37
	v_and_b32_e32 v42, 0xffff0000, v36
	v_pk_add_f32 v[36:37], v[40:41], v[42:43]
	s_nop 0
	v_add_f32_e32 v36, v36, v37
	v_add_f32_e32 v77, 0, v36
	v_lshlrev_b32_e32 v37, 16, v39
	v_lshlrev_b32_e32 v36, 16, v38
	v_and_b32_e32 v39, 0xffff0000, v39
	v_and_b32_e32 v38, 0xffff0000, v38
	v_pk_add_f32 v[44:45], v[36:37], v[38:39]
	s_nop 0
	v_pk_add_f32 v[44:45], v[44:45], v[44:45] op_sel_hi:[0,1]
	v_mov_b32_e32 v69, v45
	v_pk_add_f32 v[44:45], v[68:69], v[76:77]
	s_nop 0
	v_pk_add_f32 v[44:45], v[46:47], v[44:45]
	s_nop 0
	v_add_f32_e32 v44, v44, v45
	ds_bpermute_b32 v45, v121, v44
	s_waitcnt lgkmcnt(0)
	v_add_f32_e32 v44, v44, v45
	ds_bpermute_b32 v45, v120, v44
	s_waitcnt lgkmcnt(0)
	v_add_f32_e32 v44, v44, v45
	ds_bpermute_b32 v45, v119, v44
	s_waitcnt lgkmcnt(0)
	v_add_f32_e32 v44, v44, v45
	ds_bpermute_b32 v45, v118, v44
	s_waitcnt lgkmcnt(0)
; __device__ __forceinline__ u32x4 pack8(f32x4 a, f32x4 b) { u32x4 w; w.x = cvt_pk_bf16(a[0], a[1]); w.y = cvt_pk_bf16(a[2], a[3]); w.z = cvt_pk_bf16(b[0], b[1]); w.w = cvt_pk_bf16(b[2], b[3]); return w; }
; #define lane lane_id_asm()
; template <int NR> __device__ __forceinline__ void ln_rows(const bf16* (&zr)[NR], bf16* (&ob)[NR], float* (&of)[NR], const float* g, const float* bt, int lane) {
;     ...
;     for (int r = 0; r < NR; ++r) { float s = 0.f;
; #pragma unroll
;         for (int j = 0; j < 4; ++j) s += (v[r][j].x + v[r][j].y) + (v[r][j].z + v[r][j].w);
;         const float mean = wave_sum(s) * (1.f / 1024.f); float s2 = 0.f;
; #pragma unroll
;         for (int j = 0; j < 4; ++j) { v[r][j] = v[r][j] - mean; s2 += (v[r][j].x * v[r][j].x + v[r][j].y * v[r][j].y) + (v[r][j].z * v[r][j].z + v[r][j].w * v[r][j].w); }
;         const float rstd = 1.f / sqrtf(wave_sum(s2) * (1.f / 1024.f) + LN_EPS);
; #pragma unroll
;         for (int j = 0; j < 4; ++j) v[r][j] = v[r][j] * rstd * gg[j] + bb[j];
;         if (ob[r]) { *((v4u*)ob[r] + lane) = epi::pack8(v[r][0], v[r][1]); *((v4u*)ob[r] + 64 + lane) = epi::pack8(v[r][2], v[r][3]); }
	v_add_f32_e32 v44, v44, v45
	ds_bpermute_b32 v45, v117, v44
	s_waitcnt lgkmcnt(0)
	v_add_f32_e32 v44, v44, v45
	ds_bpermute_b32 v45, v116, v44
	s_waitcnt lgkmcnt(0)
	v_add_f32_e32 v57, v44, v45
	v_fmac_f32_e32 v42, 0xba800000, v57
	v_fmac_f32_e32 v43, 0xba800000, v57
	v_fmac_f32_e32 v41, 0xba800000, v57
	v_fmac_f32_e32 v40, 0xba800000, v57
	v_mov_b32_e32 v44, v41
	v_mov_b32_e32 v45, v43
	v_mov_b32_e32 v41, v42
	v_pk_mul_f32 v[46:47], v[44:45], v[44:45]
	v_pk_mul_f32 v[42:43], v[40:41], v[40:41]
	v_fmac_f32_e32 v38, 0xba800000, v57
	v_fmac_f32_e32 v39, 0xba800000, v57
	v_fmac_f32_e32 v37, 0xba800000, v57
	v_pk_mov_b32 v[80:81], v[42:43], v[46:47] op_sel:[1,0]
	v_mov_b32_e32 v43, v47
	v_fmac_f32_e32 v36, 0xba800000, v57
	v_mov_b32_e32 v46, v37
	v_mov_b32_e32 v47, v39
	v_mov_b32_e32 v37, v38
	v_pk_add_f32 v[42:43], v[80:81], v[42:43]
	v_pk_mul_f32 v[80:81], v[46:47], v[46:47]
	v_pk_mul_f32 v[38:39], v[36:37], v[36:37]
	v_fmac_f32_e32 v72, 0xba800000, v57
	v_pk_mov_b32 v[82:83], v[38:39], v[80:81] op_sel:[1,0]
	v_mov_b32_e32 v39, v81
	v_pk_add_f32 v[38:39], v[82:83], v[38:39]
	v_fmac_f32_e32 v73, 0xba800000, v57
	v_pk_add_f32 v[38:39], v[38:39], v[38:39] op_sel_hi:[0,1]
	v_fmac_f32_e32 v74, 0xba800000, v57
	v_mul_f32_e32 v38, v72, v72
	v_fmac_f32_e32 v75, 0xba800000, v57
	v_pk_fma_f32 v[80:81], v[72:73], v[72:73], v[38:39] op_sel_hi:[1,1,0]
	v_mul_f32_e32 v38, v74, v74
	v_pk_add_f32 v[42:43], v[42:43], v[42:43] op_sel_hi:[0,1]
	v_pk_fma_f32 v[82:83], v[74:75], v[74:75], v[38:39] op_sel_hi:[1,1,0]
	v_fmac_f32_e32 v76, 0xba800000, v57
	v_fmac_f32_e32 v68, 0xba800000, v57
	v_fmac_f32_e32 v78, 0xba800000, v57
	v_fmac_f32_e32 v70, 0xba800000, v57
	v_mul_f32_e32 v80, v70, v70
	v_mul_f32_e32 v82, v78, v78
	v_mul_f32_e32 v42, v68, v68
	v_mul_f32_e32 v38, v76, v76
	v_pk_add_f32 v[80:81], v[80:81], v[82:83]
	v_pk_add_f32 v[38:39], v[42:43], v[38:39]
	v_mov_b32_e32 v71, v78
	v_pk_add_f32 v[38:39], v[80:81], v[38:39]
	v_mov_b32_e32 v69, v76
	v_add_f32_e32 v38, v38, v39
	ds_bpermute_b32 v39, v121, v38
	s_waitcnt lgkmcnt(0)
	v_add_f32_e32 v38, v38, v39
	ds_bpermute_b32 v39, v120, v38
	s_waitcnt lgkmcnt(0)
	v_add_f32_e32 v38, v38, v39
	ds_bpermute_b32 v39, v119, v38
	s_waitcnt lgkmcnt(0)
	v_add_f32_e32 v38, v38, v39
	ds_bpermute_b32 v39, v118, v38
	s_waitcnt lgkmcnt(0)
	v_add_f32_e32 v38, v38, v39
	ds_bpermute_b32 v39, v117, v38
	s_waitcnt lgkmcnt(0)
	v_add_f32_e32 v38, v38, v39
	ds_bpermute_b32 v39, v116, v38
	s_waitcnt lgkmcnt(0)
	v_add_f32_e32 v38, v38, v39
	v_fmamk_f32 v38, v38, 0x3a800000, v106
	v_cmp_gt_f32_e32 vcc, s18, v38
	v_mul_f32_e32 v39, 0x4f800000, v38
	s_nop 0
	v_cndmask_b32_e32 v38, v38, v39, vcc
	v_sqrt_f32_e32 v39, v38
	s_nop 0
	v_add_u32_e32 v42, -1, v39
	v_fma_f32 v43, -v42, v39, v38
	v_cmp_ge_f32_e64 s[42:43], 0, v43
	v_add_u32_e32 v43, 1, v39
	s_nop 0
	v_cndmask_b32_e64 v42, v39, v42, s[42:43]
	v_fma_f32 v39, -v43, v39, v38
	v_cmp_lt_f32_e64 s[42:43], 0, v39
	s_nop 1
	v_cndmask_b32_e64 v39, v42, v43, s[42:43]
	v_mul_f32_e32 v42, 0x37800000, v39
	v_cndmask_b32_e32 v39, v39, v42, vcc
	v_cmp_class_f32_e32 vcc, v38, v107
	s_nop 1
	v_cndmask_b32_e32 v38, v39, v38, vcc
	v_div_scale_f32 v39, s[12:13], v38, v38, 1.0
	v_rcp_f32_e32 v42, v39
	s_nop 0
	v_fma_f32 v43, -v39, v42, 1.0
	v_fmac_f32_e32 v42, v43, v42
	v_div_scale_f32 v43, vcc, 1.0, v38, 1.0
	v_mul_f32_e32 v57, v43, v42
	v_fma_f32 v59, -v39, v57, v43
	v_fmac_f32_e32 v57, v59, v42
	v_fma_f32 v39, -v39, v57, v43
	v_div_fmas_f32 v39, v39, v42, v57
	v_div_fixup_f32 v38, v39, v38, 1.0
	v_pk_mul_f32 v[36:37], v[36:37], v[38:39] op_sel_hi:[1,0]
	v_pk_mul_f32 v[40:41], v[40:41], v[38:39] op_sel_hi:[1,0]
	v_pk_mul_f32 v[42:43], v[44:45], v[38:39] op_sel_hi:[1,0]
	v_pk_mul_f32 v[44:45], v[46:47], v[38:39] op_sel_hi:[1,0]
	v_pk_fma_f32 v[46:47], v[8:9], v[36:37], v[16:17]
	v_pk_mul_f32 v[36:37], v[72:73], v[38:39] op_sel_hi:[1,0]
	v_pk_fma_f32 v[40:41], v[24:25], v[40:41], v[28:29]
	v_pk_mul_f32 v[72:73], v[74:75], v[38:39] op_sel_hi:[1,0]
	v_pk_fma_f32 v[74:75], v[12:13], v[36:37], v[20:21]
	v_pk_mul_f32 v[36:37], v[70:71], v[38:39] op_sel_hi:[1,0]
	v_pk_mul_f32 v[38:39], v[68:69], v[38:39] op_sel_hi:[1,0]
	v_pk_fma_f32 v[42:43], v[26:27], v[42:43], v[30:31]
	v_pk_fma_f32 v[44:45], v[10:11], v[44:45], v[18:19]
	v_pk_fma_f32 v[68:69], v[2:3], v[38:39], v[6:7]
	v_pk_fma_f32 v[70:71], v[0:1], v[36:37], v[4:5]
	v_cvt_pk_bf16_f32 v36, v40, v41
	v_cvt_pk_bf16_f32 v37, v42, v43
	v_cvt_pk_bf16_f32 v38, v46, v47
	v_cvt_pk_bf16_f32 v39, v44, v45
	v_lshl_add_u64 v[40:41], v[54:55], 0, s[14:15]
	v_pk_fma_f32 v[72:73], v[14:15], v[72:73], v[22:23]
	global_store_dwordx4 v[40:41], v[36:39], off
	v_add_f32_e32 v59, v62, v63
	v_pk_add_f32 v[42:43], v[58:59], v[64:65]
	v_cvt_pk_bf16_f32 v36, v74, v75
	v_cvt_pk_bf16_f32 v37, v72, v73
	v_cvt_pk_bf16_f32 v38, v70, v71
	v_cvt_pk_bf16_f32 v39, v68, v69
	global_store_dwordx4 v[40:41], v[36:39], off offset:1024
	s_nop 1
	v_lshlrev_b32_e32 v37, 16, v33
	v_lshlrev_b32_e32 v36, 16, v32
	v_and_b32_e32 v39, 0xffff0000, v33
	v_and_b32_e32 v38, 0xffff0000, v32
	v_pk_add_f32 v[32:33], v[36:37], v[38:39]
	s_nop 0
	v_add_f32_e32 v32, v32, v33
	v_add_f32_e32 v61, 0, v32
	v_lshlrev_b32_e32 v33, 16, v35
	v_lshlrev_b32_e32 v32, 16, v34
	v_and_b32_e32 v35, 0xffff0000, v35
	v_and_b32_e32 v34, 0xffff0000, v34
	v_pk_add_f32 v[40:41], v[32:33], v[34:35]
	s_nop 0
	v_pk_add_f32 v[40:41], v[40:41], v[40:41] op_sel_hi:[0,1]
	v_mov_b32_e32 v57, v41
	v_pk_add_f32 v[40:41], v[56:57], v[60:61]
	s_nop 0
	v_pk_add_f32 v[40:41], v[42:43], v[40:41]
	s_nop 0
	v_add_f32_e32 v40, v40, v41
	ds_bpermute_b32 v41, v121, v40
	s_waitcnt lgkmcnt(0)
; __device__ __forceinline__ u32x4 pack8(f32x4 a, f32x4 b) { u32x4 w; w.x = cvt_pk_bf16(a[0], a[1]); w.y = cvt_pk_bf16(a[2], a[3]); w.z = cvt_pk_bf16(b[0], b[1]); w.w = cvt_pk_bf16(b[2], b[3]); return w; }
; #define lane lane_id_asm()
; template <int NR> __device__ __forceinline__ void ln_rows(const bf16* (&zr)[NR], bf16* (&ob)[NR], float* (&of)[NR], const float* g, const float* bt, int lane) {
;     ...
;     for (int r = 0; r < NR; ++r) { float s = 0.f;
; #pragma unroll
;         for (int j = 0; j < 4; ++j) s += (v[r][j].x + v[r][j].y) + (v[r][j].z + v[r][j].w);
;         const float mean = wave_sum(s) * (1.f / 1024.f); float s2 = 0.f;
; #pragma unroll
;         for (int j = 0; j < 4; ++j) { v[r][j] = v[r][j] - mean; s2 += (v[r][j].x * v[r][j].x + v[r][j].y * v[r][j].y) + (v[r][j].z * v[r][j].z + v[r][j].w * v[r][j].w); }
;         const float rstd = 1.f / sqrtf(wave_sum(s2) * (1.f / 1024.f) + LN_EPS);
; #pragma unroll
;         for (int j = 0; j < 4; ++j) v[r][j] = v[r][j] * rstd * gg[j] + bb[j];
;         if (ob[r]) { *((v4u*)ob[r] + lane) = epi::pack8(v[r][0], v[r][1]); *((v4u*)ob[r] + 64 + lane) = epi::pack8(v[r][2], v[r][3]); }
;         if (of[r]) { f32x4* o = (f32x4*)of[r]; __builtin_nontemporal_store(v[r][0], o + 2 * lane); __builtin_nontemporal_store(v[r][1], o + 2 * lane + 1); __builtin_nontemporal_store(v[r][2], o + 128 + 2 * lane); __builtin_nontemporal_store(v[r][3], o + 128 + 2 * lane + 1); } }
; }
	v_add_f32_e32 v40, v40, v41
	ds_bpermute_b32 v41, v120, v40
	s_waitcnt lgkmcnt(0)
	v_add_f32_e32 v40, v40, v41
	ds_bpermute_b32 v41, v119, v40
	s_waitcnt lgkmcnt(0)
	v_add_f32_e32 v40, v40, v41
	ds_bpermute_b32 v41, v118, v40
	s_waitcnt lgkmcnt(0)
	v_add_f32_e32 v40, v40, v41
	ds_bpermute_b32 v41, v117, v40
	s_waitcnt lgkmcnt(0)
	v_add_f32_e32 v40, v40, v41
	ds_bpermute_b32 v41, v116, v40
	s_waitcnt lgkmcnt(0)
	v_add_f32_e32 v57, v40, v41
	v_fmac_f32_e32 v38, 0xba800000, v57
	v_fmac_f32_e32 v39, 0xba800000, v57
	v_fmac_f32_e32 v37, 0xba800000, v57
	v_fmac_f32_e32 v36, 0xba800000, v57
	v_mov_b32_e32 v40, v37
	v_mov_b32_e32 v41, v39
	v_mov_b32_e32 v37, v38
	v_pk_mul_f32 v[42:43], v[40:41], v[40:41]
	v_pk_mul_f32 v[38:39], v[36:37], v[36:37]
	v_fmac_f32_e32 v34, 0xba800000, v57
	v_fmac_f32_e32 v35, 0xba800000, v57
	v_fmac_f32_e32 v33, 0xba800000, v57
	v_pk_mov_b32 v[44:45], v[38:39], v[42:43] op_sel:[1,0]
	v_mov_b32_e32 v39, v43
	v_fmac_f32_e32 v32, 0xba800000, v57
	v_mov_b32_e32 v42, v33
	v_mov_b32_e32 v43, v35
	v_mov_b32_e32 v33, v34
	v_pk_add_f32 v[38:39], v[44:45], v[38:39]
	v_pk_mul_f32 v[44:45], v[42:43], v[42:43]
	v_pk_mul_f32 v[34:35], v[32:33], v[32:33]
	v_fmac_f32_e32 v62, 0xba800000, v57
	v_pk_mov_b32 v[46:47], v[34:35], v[44:45] op_sel:[1,0]
	v_mov_b32_e32 v35, v45
	v_pk_add_f32 v[34:35], v[46:47], v[34:35]
	v_fmac_f32_e32 v63, 0xba800000, v57
	v_pk_add_f32 v[34:35], v[34:35], v[34:35] op_sel_hi:[0,1]
	v_fmac_f32_e32 v66, 0xba800000, v57
	v_mul_f32_e32 v34, v62, v62
	v_fmac_f32_e32 v67, 0xba800000, v57
	v_pk_fma_f32 v[44:45], v[62:63], v[62:63], v[34:35] op_sel_hi:[1,1,0]
	v_mul_f32_e32 v34, v66, v66
	v_pk_add_f32 v[38:39], v[38:39], v[38:39] op_sel_hi:[0,1]
	v_pk_fma_f32 v[46:47], v[66:67], v[66:67], v[34:35] op_sel_hi:[1,1,0]
	v_fmac_f32_e32 v60, 0xba800000, v57
	v_fmac_f32_e32 v56, 0xba800000, v57
	v_fmac_f32_e32 v64, 0xba800000, v57
	v_fmac_f32_e32 v58, 0xba800000, v57
	v_mul_f32_e32 v44, v58, v58
	v_mul_f32_e32 v46, v64, v64
	v_mul_f32_e32 v38, v56, v56
	v_mul_f32_e32 v34, v60, v60
	v_pk_add_f32 v[44:45], v[44:45], v[46:47]
	v_pk_add_f32 v[34:35], v[38:39], v[34:35]
	v_mov_b32_e32 v59, v64
	v_pk_add_f32 v[34:35], v[44:45], v[34:35]
	v_mov_b32_e32 v57, v60
	v_add_f32_e32 v34, v34, v35
	ds_bpermute_b32 v35, v121, v34
	s_waitcnt lgkmcnt(0)
	v_add_f32_e32 v34, v34, v35
	ds_bpermute_b32 v35, v120, v34
	s_waitcnt lgkmcnt(0)
	v_add_f32_e32 v34, v34, v35
	ds_bpermute_b32 v35, v119, v34
	s_waitcnt lgkmcnt(0)
	v_add_f32_e32 v34, v34, v35
	ds_bpermute_b32 v35, v118, v34
	s_waitcnt lgkmcnt(0)
	v_add_f32_e32 v34, v34, v35
	ds_bpermute_b32 v35, v117, v34
	s_waitcnt lgkmcnt(0)
	v_add_f32_e32 v34, v34, v35
	ds_bpermute_b32 v35, v116, v34
	s_waitcnt lgkmcnt(0)
	v_add_f32_e32 v34, v34, v35
	v_fmamk_f32 v34, v34, 0x3a800000, v106
	v_cmp_gt_f32_e32 vcc, s18, v34
	v_mul_f32_e32 v35, 0x4f800000, v34
	s_nop 0
	v_cndmask_b32_e32 v34, v34, v35, vcc
	v_sqrt_f32_e32 v35, v34
	s_nop 0
	v_add_u32_e32 v38, -1, v35
	v_fma_f32 v39, -v38, v35, v34
	v_cmp_ge_f32_e64 s[42:43], 0, v39
	v_add_u32_e32 v39, 1, v35
	s_nop 0
	v_cndmask_b32_e64 v38, v35, v38, s[42:43]
	v_fma_f32 v35, -v39, v35, v34
	v_cmp_lt_f32_e64 s[42:43], 0, v35
	s_nop 1
	v_cndmask_b32_e64 v35, v38, v39, s[42:43]
	v_mul_f32_e32 v38, 0x37800000, v35
	v_cndmask_b32_e32 v35, v35, v38, vcc
	v_cmp_class_f32_e32 vcc, v34, v107
	s_nop 1
	v_cndmask_b32_e32 v34, v35, v34, vcc
	v_div_scale_f32 v35, s[12:13], v34, v34, 1.0
	v_rcp_f32_e32 v38, v35
	s_nop 0
	v_fma_f32 v39, -v35, v38, 1.0
	v_fmac_f32_e32 v38, v39, v38
	v_div_scale_f32 v39, vcc, 1.0, v34, 1.0
	v_mul_f32_e32 v44, v39, v38
	v_fma_f32 v45, -v35, v44, v39
	v_fmac_f32_e32 v44, v45, v38
	v_fma_f32 v35, -v35, v44, v39
	v_div_fmas_f32 v35, v35, v38, v44
	v_div_fixup_f32 v34, v35, v34, 1.0
	v_pk_mul_f32 v[36:37], v[36:37], v[34:35] op_sel_hi:[1,0]
	v_pk_mul_f32 v[38:39], v[40:41], v[34:35] op_sel_hi:[1,0]
	v_pk_fma_f32 v[24:25], v[24:25], v[36:37], v[28:29]
	v_pk_fma_f32 v[26:27], v[26:27], v[38:39], v[30:31]
	v_pk_mul_f32 v[28:29], v[32:33], v[34:35] op_sel_hi:[1,0]
	v_pk_mul_f32 v[30:31], v[42:43], v[34:35] op_sel_hi:[1,0]
	v_pk_fma_f32 v[8:9], v[8:9], v[28:29], v[16:17]
	v_pk_fma_f32 v[10:11], v[10:11], v[30:31], v[18:19]
	v_pk_mul_f32 v[16:17], v[62:63], v[34:35] op_sel_hi:[1,0]
	v_pk_mul_f32 v[18:19], v[66:67], v[34:35] op_sel_hi:[1,0]
	v_pk_fma_f32 v[12:13], v[12:13], v[16:17], v[20:21]
	v_pk_fma_f32 v[14:15], v[14:15], v[18:19], v[22:23]
	v_pk_mul_f32 v[16:17], v[58:59], v[34:35] op_sel_hi:[1,0]
	v_pk_mul_f32 v[18:19], v[56:57], v[34:35] op_sel_hi:[1,0]
	v_pk_fma_f32 v[4:5], v[0:1], v[16:17], v[4:5]
	v_pk_fma_f32 v[6:7], v[2:3], v[18:19], v[6:7]
	v_cvt_pk_bf16_f32 v0, v24, v25
	v_cvt_pk_bf16_f32 v1, v26, v27
	v_cvt_pk_bf16_f32 v2, v8, v9
	v_cvt_pk_bf16_f32 v3, v10, v11
	v_lshl_add_u64 v[8:9], v[54:55], 0, s[4:5]
	global_store_dwordx4 v[8:9], v[0:3], off
	s_nop 1
	v_cvt_pk_bf16_f32 v0, v12, v13
	v_cvt_pk_bf16_f32 v1, v14, v15
	v_cvt_pk_bf16_f32 v2, v4, v5
	v_cvt_pk_bf16_f32 v3, v6, v7
	global_store_dwordx4 v[8:9], v[0:3], off offset:1024
	s_branch .LBB0_1394
